# stack: barrier invalidate on wave 1 + dropped release waits + chain vmcnt/deferred stores + P5b scan after loads + P8 piece loads batched + attention DMA early
# speedup vs baseline: 1.0027x; 1.0027x over previous
.LBB0_848:
	s_or_b64 exec, exec, s[60:61]
	s_andn2_b64 vcc, exec, s[24:25]
	s_cbranch_vccnz .Lscan_skip
	s_load_dwordx2 s[60:61], s[22:23], 0x90
	s_load_dwordx4 s[72:75], s[22:23], 0x40
	v_mov_b32_e32 v204, s55
	v_and_b32_e32 v208, 64, v166
	v_add_u32_e32 v209, -4, v166
	s_waitcnt lgkmcnt(0)
	v_lshl_add_u64 v[202:203], s[60:61], 0, v[150:151]
	global_load_dword v205, v[202:203], off
	global_load_dword v206, v204, s[74:75]
	s_nop 0
	global_load_dword v204, v204, s[72:73]
	s_nop 0
	global_load_dword v207, v[202:203], off offset:-16
	v_add_u32_e32 v202, -1, v166
	v_add_u32_e32 v203, -2, v166
	v_cmp_lt_i32_e32 vcc, v202, v208
	v_add_u32_e32 v210, -8, v166
	v_add_u32_e32 v211, -16, v166
	v_cndmask_b32_e32 v202, v202, v166, vcc
	v_cmp_lt_i32_e32 vcc, v203, v208
	v_subrev_u32_e32 v212, 32, v166
	v_xor_b32_e32 v213, 1, v166
	v_cndmask_b32_e32 v219, v203, v166, vcc
	v_cmp_lt_i32_e32 vcc, v209, v208
	v_xor_b32_e32 v214, 2, v166
	v_xor_b32_e32 v215, 4, v166
	v_cndmask_b32_e32 v209, v209, v166, vcc
	v_cmp_lt_i32_e32 vcc, v210, v208
	v_lshlrev_b32_e32 v209, 2, v209
	v_xor_b32_e32 v216, 8, v166
	v_cndmask_b32_e32 v210, v210, v166, vcc
	v_cmp_lt_i32_e32 vcc, v211, v208
	v_lshlrev_b32_e32 v210, 2, v210
	v_xor_b32_e32 v217, 16, v166
	v_xor_b32_e32 v218, 32, v166
	s_waitcnt vmcnt(2)
	v_add_f32_e32 v203, v205, v206
	v_mul_f32_e64 v205, |v203|, s57
	v_exp_f32_e32 v205, v205
	v_cndmask_b32_e32 v206, v211, v166, vcc
	v_lshlrev_b32_e32 v211, 2, v202
	v_min_f32_e32 v220, 0, v203
	v_add_f32_e32 v221, 1.0, v205
	v_add_f32_e32 v222, -1.0, v221
	v_frexp_mant_f32_e32 v223, v221
	v_cvt_f64_f32_e32 v[202:203], v221
	v_sub_f32_e32 v224, v222, v221
	v_frexp_exp_i32_f64_e32 v202, v[202:203]
	v_cmp_gt_f32_e32 vcc, s64, v223
	v_sub_f32_e32 v222, v205, v222
	v_add_f32_e32 v203, 1.0, v224
	v_subbrev_co_u32_e32 v202, vcc, 0, v202, vcc
	v_add_f32_e32 v203, v222, v203
	v_sub_u32_e32 v222, 0, v202
	v_cvt_f32_i32_e32 v202, v202
	v_ldexp_f32 v221, v221, v222
	v_ldexp_f32 v203, v203, v222
	v_add_f32_e32 v222, -1.0, v221
	v_add_f32_e32 v223, 1.0, v221
	v_add_f32_e32 v224, 1.0, v222
	v_add_f32_e32 v225, -1.0, v223
	v_sub_f32_e32 v224, v221, v224
	v_sub_f32_e32 v221, v221, v225
	v_mul_f32_e32 v225, 0x3f317218, v202
	v_add_f32_e32 v224, v203, v224
	v_add_f32_e32 v203, v203, v221
	v_fma_f32 v221, v202, s65, -v225
	v_add_f32_e32 v226, v222, v224
	v_add_f32_e32 v227, v223, v203
	v_fmac_f32_e32 v221, 0xb102e308, v202
	v_sub_f32_e32 v202, v226, v222
	v_sub_f32_e32 v222, v227, v223
	v_rcp_f32_e32 v223, v227
	v_add_f32_e32 v228, v225, v221
	v_sub_f32_e32 v203, v203, v222
	v_sub_f32_e32 v222, v228, v225
	v_sub_f32_e32 v221, v221, v222
	v_mul_f32_e32 v222, v226, v223
	v_sub_f32_e32 v202, v224, v202
	v_mul_f32_e32 v224, v227, v222
	v_fma_f32 v225, v222, v227, -v224
	v_fmac_f32_e32 v225, v222, v203
	v_add_f32_e32 v229, v224, v225
	v_sub_f32_e32 v230, v226, v229
	v_sub_f32_e32 v224, v229, v224
	v_sub_f32_e32 v226, v226, v230
	v_sub_f32_e32 v224, v224, v225
	v_sub_f32_e32 v225, v226, v229
	v_add_f32_e32 v202, v202, v225
	v_add_f32_e32 v202, v224, v202
	v_add_f32_e32 v224, v230, v202
	v_mul_f32_e32 v225, v223, v224
	v_sub_f32_e32 v226, v230, v224
	v_mul_f32_e32 v229, v227, v225
	v_add_f32_e32 v202, v202, v226
	v_add_f32_e32 v226, v222, v225
	v_fma_f32 v227, v225, v227, -v229
	v_sub_f32_e32 v222, v226, v222
	v_fmac_f32_e32 v227, v225, v203
	v_sub_f32_e32 v203, v225, v222
	v_add_f32_e32 v222, v229, v227
	v_sub_f32_e32 v225, v222, v229
	v_sub_f32_e32 v229, v224, v222
	v_sub_f32_e32 v224, v224, v229
	v_sub_f32_e32 v222, v224, v222
	v_sub_f32_e32 v225, v225, v227
	v_add_f32_e32 v202, v202, v222
	v_add_f32_e32 v202, v225, v202
	v_add_f32_e32 v202, v229, v202
	v_mul_f32_e32 v202, v223, v202
	v_add_f32_e32 v202, v203, v202
	v_add_f32_e32 v203, v226, v202
	v_mul_f32_e32 v222, v203, v203
	v_fmamk_f32 v225, v222, 0x3e9b6dac, v158
	v_sub_f32_e32 v223, v203, v226
	v_ldexp_f32 v224, v203, 1
	v_mul_f32_e32 v203, v203, v222
	v_fmaak_f32 v222, v222, v225, 0x3f2aaada
	v_mul_f32_e32 v203, v203, v222
	v_add_f32_e32 v222, v224, v203
	v_sub_f32_e32 v202, v202, v223
	v_sub_f32_e32 v223, v222, v224
	v_ldexp_f32 v202, v202, 1
	v_sub_f32_e32 v203, v203, v223
	v_add_f32_e32 v202, v202, v203
	v_add_f32_e32 v203, v222, v202
	v_sub_f32_e32 v222, v203, v222
	v_add_f32_e32 v223, v228, v203
	v_sub_f32_e32 v202, v202, v222
	v_sub_f32_e32 v222, v223, v228
	v_sub_f32_e32 v224, v223, v222
	v_sub_f32_e32 v203, v203, v222
	v_add_f32_e32 v222, v221, v202
	v_sub_f32_e32 v224, v228, v224
	v_sub_f32_e32 v225, v222, v221
	v_add_f32_e32 v203, v203, v224
	v_sub_f32_e32 v224, v222, v225
	v_sub_f32_e32 v202, v202, v225
	v_sub_f32_e32 v221, v221, v224
	v_add_f32_e32 v203, v222, v203
	v_add_f32_e32 v202, v202, v221
	v_add_f32_e32 v221, v223, v203
	v_sub_f32_e32 v222, v221, v223
	v_sub_f32_e32 v203, v203, v222
	v_add_f32_e32 v202, v202, v203
	v_add_f32_e32 v202, v221, v202
	v_cmp_neq_f32_e32 vcc, s66, v205
	s_waitcnt vmcnt(0)
	v_add_f32_e32 v204, v207, v204
	v_cndmask_b32_e32 v202, v163, v202, vcc
	v_cmp_ngt_f32_e32 vcc, -1.0, v205
	s_nop 1
	v_cndmask_b32_e32 v202, v164, v202, vcc
	v_cmp_neq_f32_e32 vcc, -1.0, v205
	s_nop 1
	v_cndmask_b32_e32 v202, v165, v202, vcc
	v_cmp_lt_f32_e64 vcc, |v205|, s67
	s_nop 1
	v_cndmask_b32_e32 v202, v202, v205, vcc
	v_sub_f32_e32 v202, v220, v202
	ds_bpermute_b32 v203, v211, v202
	v_cmp_lt_i32_e32 vcc, v212, v208
	v_add_u32_e32 v208, 64, v208
	s_waitcnt lgkmcnt(0)
	v_add_f32_e32 v203, v202, v203
	v_cndmask_b32_e32 v205, v212, v166, vcc
	v_lshlrev_b32_e32 v212, 2, v219
	v_cndmask_b32_e64 v202, v203, v202, s[8:9]
	ds_bpermute_b32 v203, v212, v202
	v_lshlrev_b32_e32 v219, 2, v206
	v_lshlrev_b32_e32 v205, 2, v205
	v_cmp_lt_i32_e32 vcc, v213, v208
	s_waitcnt lgkmcnt(0)
	v_add_f32_e32 v203, v202, v203
	v_cndmask_b32_e64 v202, v203, v202, s[10:11]
	ds_bpermute_b32 v203, v209, v202
	v_cndmask_b32_e32 v206, v166, v213, vcc
	v_cmp_lt_i32_e32 vcc, v214, v208
	s_waitcnt lgkmcnt(0)
	v_add_f32_e32 v203, v202, v203
	v_cndmask_b32_e64 v202, v203, v202, s[12:13]
	ds_bpermute_b32 v203, v210, v202
	v_cndmask_b32_e32 v213, v166, v214, vcc
	v_cmp_lt_i32_e32 vcc, v215, v208
	v_lshlrev_b32_e32 v213, 2, v213
	s_waitcnt lgkmcnt(0)
	v_add_f32_e32 v203, v202, v203
	v_cndmask_b32_e64 v202, v203, v202, s[14:15]
	ds_bpermute_b32 v203, v219, v202
	v_cndmask_b32_e32 v214, v166, v215, vcc
	v_cmp_lt_i32_e32 vcc, v216, v208
	v_lshlrev_b32_e32 v214, 2, v214
	s_waitcnt lgkmcnt(0)
	v_add_f32_e32 v203, v202, v203
	v_cndmask_b32_e64 v202, v203, v202, s[16:17]
	ds_bpermute_b32 v203, v205, v202
	v_cndmask_b32_e32 v215, v166, v216, vcc
	v_cmp_lt_i32_e32 vcc, v217, v208
	v_lshlrev_b32_e32 v215, 2, v215
	s_waitcnt lgkmcnt(0)
	v_add_f32_e32 v203, v202, v203
	v_cndmask_b32_e32 v216, v166, v217, vcc
	v_cmp_lt_i32_e32 vcc, v218, v208
	v_lshlrev_b32_e32 v217, 2, v206
	v_lshlrev_b32_e32 v216, 2, v216
	v_cndmask_b32_e32 v208, v166, v218, vcc
	v_cndmask_b32_e64 v218, v203, v202, s[18:19]
	v_sub_f32_e32 v203, v204, v218
	ds_bpermute_b32 v202, v167, v218
	ds_bpermute_b32 v211, v211, v203
	v_lshlrev_b32_e32 v220, 2, v208
	v_lshl_add_u64 v[206:207], s[60:61], 0, v[148:149]
	s_waitcnt lgkmcnt(1)
	v_sub_f32_e32 v208, v202, v218
	s_waitcnt lgkmcnt(0)
	v_max_f32_e32 v211, v211, v211
	v_add_f32_e32 v204, v204, v208
	v_max_f32_e32 v208, v203, v211
	ds_bpermute_b32 v211, v217, v204
	v_cndmask_b32_e64 v203, v208, v203, s[8:9]
	ds_bpermute_b32 v212, v212, v203
	v_add_co_u32_e32 v208, vcc, 0xffff8000, v206
	s_waitcnt lgkmcnt(1)
	v_max_f32_e32 v211, v211, v211
	v_max_f32_e32 v211, v204, v211
	s_waitcnt lgkmcnt(0)
	v_max_f32_e32 v212, v212, v212
	ds_bpermute_b32 v213, v213, v211
	v_max_f32_e32 v212, v203, v212
	v_cndmask_b32_e64 v203, v212, v203, s[10:11]
	ds_bpermute_b32 v212, v209, v203
	v_mul_f32_e32 v204, 0x3fb8aa3b, v204
	s_waitcnt lgkmcnt(1)
	v_max_f32_e32 v213, v213, v213
	v_max_f32_e32 v211, v211, v213
	ds_bpermute_b32 v213, v214, v211
	s_waitcnt lgkmcnt(1)
	v_max_f32_e32 v212, v212, v212
	v_max_f32_e32 v212, v203, v212
	v_cndmask_b32_e64 v203, v212, v203, s[12:13]
	ds_bpermute_b32 v210, v210, v203
	s_waitcnt lgkmcnt(1)
	v_max_f32_e32 v212, v213, v213
	v_max_f32_e32 v211, v211, v212
	ds_bpermute_b32 v212, v215, v211
	v_exp_f32_e32 v213, v204
	s_waitcnt lgkmcnt(1)
	v_max_f32_e32 v210, v210, v210
	v_max_f32_e32 v210, v203, v210
	v_cndmask_b32_e64 v203, v210, v203, s[14:15]
	ds_bpermute_b32 v210, v219, v203
	s_waitcnt lgkmcnt(1)
	v_max_f32_e32 v204, v212, v212
	v_max_f32_e32 v204, v211, v204
	ds_bpermute_b32 v211, v216, v204
	v_addc_co_u32_e32 v209, vcc, -1, v207, vcc
	s_waitcnt lgkmcnt(1)
	v_max_f32_e32 v210, v210, v210
	v_max_f32_e32 v210, v203, v210
	v_cndmask_b32_e64 v210, v210, v203, s[16:17]
	ds_bpermute_b32 v205, v205, v210
	s_waitcnt lgkmcnt(1)
	v_max_f32_e32 v203, v211, v211
	v_max_f32_e32 v203, v204, v203
	ds_bpermute_b32 v204, v220, v203
	v_max_f32_e32 v211, v210, v210
	s_waitcnt lgkmcnt(1)
	v_max_f32_e32 v205, v205, v205
	v_max_f32_e32 v205, v211, v205
	v_cndmask_b32_e64 v205, v205, v210, s[18:19]
	global_store_dword v[208:209], v218, off
	global_store_dword v[206:207], v205, off
	ds_write_b32 v156, v213 offset:34816
	s_and_saveexec_b64 s[62:63], s[8:9]
	s_cbranch_execz .LBB0_852
	s_add_u32 s60, s60, s50
	s_waitcnt lgkmcnt(1)
	v_max_f32_e32 v204, v204, v204
	v_max_f32_e32 v203, v203, v203
	s_addc_u32 s61, s61, s51
	v_max_f32_e32 v203, v203, v204
	global_store_dwordx2 v127, v[202:203], s[60:61]

.Lscan_skip:
	global_load_dwordx4 v[26:29], v[128:129], off offset:16
	global_load_dwordx4 v[30:33], v[128:129], off
	global_load_dwordx4 v[58:61], v[142:143], off offset:16
	global_load_dwordx4 v[90:93], v[142:143], off
	global_load_dwordx4 v[42:45], v[128:129], off offset:2064
	global_load_dwordx4 v[66:69], v[128:129], off offset:2048
	global_load_dwordx4 v[62:65], v[142:143], off offset:2064
	global_load_dwordx4 v[94:97], v[142:143], off offset:2048
	global_load_dwordx4 v[50:53], v[130:131], off offset:16
	global_load_dwordx4 v[86:89], v[130:131], off
	global_load_dwordx4 v[46:49], v[132:133], off offset:16
	global_load_dwordx4 v[78:81], v[132:133], off
	v_lshl_add_u64 v[10:11], s[26:27], 0, v[146:147]
	v_lshl_add_u64 v[12:13], v[10:11], 0, s[36:37]
	v_add_co_u32_e32 v10, vcc, 0xb000000, v10
	s_waitcnt vmcnt(13)
	v_lshlrev_b32_e32 v178, 16, v119
	v_addc_co_u32_e32 v11, vcc, 0, v11, vcc
	global_load_dwordx4 v[70:73], v[134:135], off
	global_load_dwordx4 v[168:171], v[10:11], off
	global_load_dwordx4 v[172:175], v[12:13], off offset:16
	global_load_dwordx4 v[82:85], v[134:135], off offset:16
	global_load_dwordx4 v[74:77], v[136:137], off
	global_load_dwordx4 v[54:57], v[136:137], off offset:16
	global_load_dwordx4 v[22:25], v[138:139], off offset:16
	global_load_dwordx4 v[34:37], v[138:139], off
	global_load_dwordx4 v[10:13], v[140:141], off offset:16
	global_load_dwordx4 v[18:21], v[140:141], off
	v_and_b32_e32 v179, 0xffff0000, v119
	v_lshlrev_b32_e32 v180, 16, v120
	v_and_b32_e32 v181, 0xffff0000, v120
	v_lshlrev_b32_e32 v182, 16, v121
	v_and_b32_e32 v183, 0xffff0000, v121
	s_waitcnt vmcnt(22)
	v_lshlrev_b32_e32 v184, 16, v102
	v_and_b32_e32 v185, 0xffff0000, v102
	v_lshlrev_b32_e32 v186, 16, v103
	v_and_b32_e32 v187, 0xffff0000, v103
	v_lshlrev_b32_e32 v188, 16, v104
	v_and_b32_e32 v189, 0xffff0000, v104
	v_lshlrev_b32_e32 v190, 16, v105
	v_and_b32_e32 v191, 0xffff0000, v105
	v_lshlrev_b32_e32 v102, 16, v114
	v_and_b32_e32 v103, 0xffff0000, v114
	v_lshlrev_b32_e32 v104, 16, v115
	v_and_b32_e32 v105, 0xffff0000, v115
	v_lshlrev_b32_e32 v114, 16, v116
	v_and_b32_e32 v115, 0xffff0000, v116
	v_lshlrev_b32_e32 v176, 16, v118
	v_and_b32_e32 v177, 0xffff0000, v118
	v_lshlrev_b32_e32 v116, 16, v117
	v_and_b32_e32 v117, 0xffff0000, v117
	v_lshlrev_b32_e32 v118, 16, v38
	v_and_b32_e32 v119, 0xffff0000, v38
	v_lshlrev_b32_e32 v38, 16, v39
	v_and_b32_e32 v39, 0xffff0000, v39
	v_lshlrev_b32_e32 v154, 16, v106
	v_and_b32_e32 v155, 0xffff0000, v106
	v_lshlrev_b32_e32 v106, 16, v107
	v_and_b32_e32 v107, 0xffff0000, v107
	v_lshlrev_b32_e32 v120, 16, v40
	v_and_b32_e32 v121, 0xffff0000, v40
	v_lshlrev_b32_e32 v40, 16, v41
	v_and_b32_e32 v41, 0xffff0000, v41
	v_lshlrev_b32_e32 v194, 16, v14
	v_and_b32_e32 v195, 0xffff0000, v14
	v_lshlrev_b32_e32 v196, 16, v15
	v_and_b32_e32 v197, 0xffff0000, v15
	v_lshlrev_b32_e32 v198, 16, v16
	v_and_b32_e32 v199, 0xffff0000, v16
	v_lshlrev_b32_e32 v200, 16, v17
	v_and_b32_e32 v201, 0xffff0000, v17
	v_lshlrev_b32_e32 v192, 16, v112
	v_and_b32_e32 v193, 0xffff0000, v112
	v_lshlrev_b32_e32 v112, 16, v113
	v_and_b32_e32 v113, 0xffff0000, v113
	v_lshl_add_u64 v[146:147], v[146:147], 0, s[42:43]
	v_lshl_add_u64 v[148:149], v[148:149], 0, s[58:59]
	v_lshl_add_u64 v[150:151], v[150:151], 0, s[34:35]
	s_waitcnt vmcnt(8)
	ds_write_b128 v159, v[168:171] offset:17408
	s_waitcnt vmcnt(7)
	ds_write_b128 v159, v[172:175] offset:17424
	v_pk_fma_f32 v[178:179], v[32:33], v[178:179], v[92:93]
	v_pk_fma_f32 v[180:181], v[26:27], v[180:181], v[58:59]
	v_pk_fma_f32 v[182:183], v[28:29], v[182:183], v[60:61]
	v_pk_fma_f32 v[184:185], v[66:67], v[184:185], v[94:95]
	v_pk_fma_f32 v[186:187], v[68:69], v[186:187], v[96:97]
	v_pk_fma_f32 v[178:179], v[88:89], v[104:105], v[178:179]
	v_pk_fma_f32 v[180:181], v[50:51], v[114:115], v[180:181]
	v_lshlrev_b32_e32 v170, 16, v108
	v_and_b32_e32 v171, 0xffff0000, v108
	v_pk_fma_f32 v[176:177], v[30:31], v[176:177], v[90:91]
	v_pk_fma_f32 v[188:189], v[42:43], v[188:189], v[62:63]
	v_pk_fma_f32 v[190:191], v[44:45], v[190:191], v[64:65]
	v_pk_fma_f32 v[182:183], v[52:53], v[116:117], v[182:183]
	v_pk_fma_f32 v[186:187], v[80:81], v[38:39], v[186:187]
	v_pk_fma_f32 v[184:185], v[78:79], v[118:119], v[184:185]
	v_pk_fma_f32 v[168:169], v[72:73], v[106:107], v[178:179]
	v_lshlrev_b32_e32 v108, 16, v109
	v_and_b32_e32 v109, 0xffff0000, v109
	s_waitcnt vmcnt(6)
	v_pk_fma_f32 v[172:173], v[82:83], v[170:171], v[180:181]
	v_lshlrev_b32_e32 v178, 16, v98
	v_and_b32_e32 v179, 0xffff0000, v98
	v_lshlrev_b32_e32 v180, 16, v99
	v_and_b32_e32 v181, 0xffff0000, v99
	v_pk_fma_f32 v[176:177], v[86:87], v[102:103], v[176:177]
	v_pk_fma_f32 v[190:191], v[48:49], v[40:41], v[190:191]
	v_pk_fma_f32 v[188:189], v[46:47], v[120:121], v[188:189]
	v_pk_fma_f32 v[174:175], v[84:85], v[108:109], v[182:183]
	s_waitcnt vmcnt(5)
	v_pk_fma_f32 v[98:99], v[74:75], v[178:179], v[184:185]
	v_pk_fma_f32 v[182:183], v[76:77], v[180:181], v[186:187]
	v_lshlrev_b32_e32 v184, 16, v100
	v_and_b32_e32 v185, 0xffff0000, v100
	v_lshlrev_b32_e32 v186, 16, v101
	v_and_b32_e32 v187, 0xffff0000, v101
	v_pk_fma_f32 v[176:177], v[70:71], v[154:155], v[176:177]
	s_waitcnt vmcnt(4)
	v_pk_fma_f32 v[100:101], v[54:55], v[184:185], v[188:189]
	v_pk_fma_f32 v[188:189], v[56:57], v[186:187], v[190:191]
	v_lshlrev_b32_e32 v190, 16, v110
	v_and_b32_e32 v191, 0xffff0000, v110
	s_waitcnt vmcnt(2)
	v_pk_fma_f32 v[176:177], v[34:35], v[190:191], v[176:177]
	v_lshlrev_b32_e32 v110, 16, v111
	v_mul_f32_e32 v14, 0xbfb8aa3b, v176
	v_mul_f32_e32 v15, 0xbfb8aa3b, v177
	v_exp_f32_e32 v14, v14
	v_exp_f32_e32 v15, v15
	v_and_b32_e32 v111, 0xffff0000, v111
	v_pk_fma_f32 v[168:169], v[36:37], v[110:111], v[168:169]
	v_add_f32_e32 v14, 1.0, v14
	v_add_f32_e32 v15, 1.0, v15
	v_rcp_f32_e32 v14, v14
	v_rcp_f32_e32 v15, v15
	v_mul_f32_e32 v16, 0xbfb8aa3b, v168
	v_exp_f32_e32 v16, v16
	v_mul_f32_e32 v17, 0xbfb8aa3b, v169
	v_exp_f32_e32 v17, v17
	v_pk_mul_f32 v[14:15], v[176:177], v[14:15]
	v_pk_fma_f32 v[172:173], v[22:23], v[192:193], v[172:173]
	v_cvt_pk_bf16_f32 v14, v14, v15
	v_add_f32_e32 v15, 1.0, v16
	v_rcp_f32_e32 v16, v15
	v_add_f32_e32 v15, 1.0, v17
	v_rcp_f32_e32 v17, v15
	v_mul_f32_e32 v15, 0xbfb8aa3b, v172
	v_exp_f32_e32 v15, v15
	v_mul_f32_e32 v126, 0xbfb8aa3b, v173
	v_exp_f32_e32 v126, v126
	v_pk_fma_f32 v[174:175], v[24:25], v[112:113], v[174:175]
	v_add_f32_e32 v15, 1.0, v15
	v_pk_mul_f32 v[16:17], v[168:169], v[16:17]
	v_rcp_f32_e32 v168, v15
	v_add_f32_e32 v15, 1.0, v126
	v_mul_f32_e32 v126, 0xbfb8aa3b, v174
	v_exp_f32_e32 v126, v126
	v_mul_f32_e32 v169, 0xbfb8aa3b, v175
	v_exp_f32_e32 v177, v169
	v_rcp_f32_e32 v169, v15
	v_add_f32_e32 v15, 1.0, v126
	v_rcp_f32_e32 v176, v15
	v_add_f32_e32 v15, 1.0, v177
	s_waitcnt vmcnt(0)
	v_pk_fma_f32 v[98:99], v[18:19], v[194:195], v[98:99]
	v_rcp_f32_e32 v177, v15
	v_cvt_pk_bf16_f32 v15, v16, v17
	v_pk_mul_f32 v[16:17], v[172:173], v[168:169]
	v_pk_fma_f32 v[182:183], v[20:21], v[196:197], v[182:183]
	v_cvt_pk_bf16_f32 v16, v16, v17
	v_mul_f32_e32 v17, 0xbfb8aa3b, v98
	v_exp_f32_e32 v126, v17
	v_mul_f32_e32 v17, 0xbfb8aa3b, v99
	v_exp_f32_e32 v172, v17
	v_pk_mul_f32 v[168:169], v[174:175], v[176:177]
	v_add_f32_e32 v126, 1.0, v126
	v_cvt_pk_bf16_f32 v17, v168, v169
	v_mul_f32_e32 v169, 0xbfb8aa3b, v182
	v_rcp_f32_e32 v168, v126
	v_add_f32_e32 v126, 1.0, v172
	v_exp_f32_e32 v172, v169
	v_mul_f32_e32 v169, 0xbfb8aa3b, v183
	v_exp_f32_e32 v173, v169
	v_rcp_f32_e32 v169, v126
	v_add_f32_e32 v126, 1.0, v172
	v_rcp_f32_e32 v172, v126
	v_add_f32_e32 v126, 1.0, v173
	v_rcp_f32_e32 v173, v126
	v_pk_mul_f32 v[98:99], v[98:99], v[168:169]
	v_pk_fma_f32 v[100:101], v[10:11], v[198:199], v[100:101]
	v_pk_mul_f32 v[98:99], v[98:99], s[38:39] op_sel_hi:[1,0]
	v_pk_mul_f32 v[168:169], v[182:183], v[172:173]
	v_cvt_pk_bf16_f32 v98, v98, v99
	v_mul_f32_e32 v99, 0xbfb8aa3b, v100
	v_exp_f32_e32 v126, v99
	v_mul_f32_e32 v99, 0xbfb8aa3b, v101
	v_exp_f32_e32 v172, v99
	v_pk_fma_f32 v[188:189], v[12:13], v[200:201], v[188:189]
	v_pk_mul_f32 v[168:169], v[168:169], s[38:39] op_sel_hi:[1,0]
	v_add_f32_e32 v126, 1.0, v126
	v_cvt_pk_bf16_f32 v99, v168, v169
	v_mul_f32_e32 v169, 0xbfb8aa3b, v188
	v_rcp_f32_e32 v168, v126
	v_add_f32_e32 v126, 1.0, v172
	v_exp_f32_e32 v172, v169
	v_mul_f32_e32 v169, 0xbfb8aa3b, v189
	v_exp_f32_e32 v173, v169
	v_rcp_f32_e32 v169, v126
	v_add_f32_e32 v126, 1.0, v172
	v_rcp_f32_e32 v172, v126
	v_add_f32_e32 v126, 1.0, v173
	v_rcp_f32_e32 v173, v126
	v_pk_mul_f32 v[100:101], v[100:101], v[168:169]
	v_pk_fma_f32 v[26:27], v[26:27], v[114:115], v[58:59]
	v_pk_mul_f32 v[100:101], v[100:101], s[38:39] op_sel_hi:[1,0]
	v_pk_mul_f32 v[168:169], v[188:189], v[172:173]
	v_cvt_pk_bf16_f32 v100, v100, v101
	v_pk_mul_f32 v[168:169], v[168:169], s[38:39] op_sel_hi:[1,0]
	v_pk_fma_f32 v[26:27], v[50:51], v[170:171], v[26:27]
	v_cvt_pk_bf16_f32 v101, v168, v169
	v_lshl_add_u64 v[168:169], s[26:27], 0, v[152:153]
	v_add_co_u32_e32 v168, vcc, s68, v168
	v_pk_fma_f32 v[26:27], v[82:83], v[192:193], v[26:27]
	s_nop 0
	v_addc_co_u32_e32 v169, vcc, 0, v169, vcc
	global_store_dwordx4 v[168:169], v[14:17], off
	v_pk_fma_f32 v[40:41], v[44:45], v[40:41], v[64:65]
	v_pk_fma_f32 v[28:29], v[28:29], v[116:117], v[60:61]
	v_pk_fma_f32 v[16:17], v[32:33], v[104:105], v[92:93]
	v_pk_fma_f32 v[14:15], v[30:31], v[102:103], v[90:91]
	v_pk_fma_f32 v[16:17], v[88:89], v[106:107], v[16:17]
	v_pk_fma_f32 v[32:33], v[68:69], v[38:39], v[96:97]
	v_pk_fma_f32 v[38:39], v[42:43], v[120:121], v[62:63]
	v_pk_fma_f32 v[14:15], v[86:87], v[154:155], v[14:15]
	v_pk_fma_f32 v[16:17], v[72:73], v[110:111], v[16:17]
	v_lshlrev_b32_e32 v42, 16, v6
	v_and_b32_e32 v43, 0xffff0000, v6
	v_lshlrev_b32_e32 v6, 16, v7
	v_and_b32_e32 v7, 0xffff0000, v7
	v_pk_fma_f32 v[30:31], v[66:67], v[118:119], v[94:95]
	v_pk_fma_f32 v[32:33], v[80:81], v[180:181], v[32:33]
	v_pk_fma_f32 v[14:15], v[70:71], v[190:191], v[14:15]
	v_pk_fma_f32 v[6:7], v[36:37], v[6:7], v[16:17]
	v_lshlrev_b32_e32 v16, 16, v8
	v_and_b32_e32 v17, 0xffff0000, v8
	v_pk_fma_f32 v[30:31], v[78:79], v[178:179], v[30:31]
	v_pk_fma_f32 v[32:33], v[76:77], v[196:197], v[32:33]
	v_pk_fma_f32 v[14:15], v[34:35], v[42:43], v[14:15]
	v_pk_fma_f32 v[16:17], v[22:23], v[16:17], v[26:27]
	v_lshlrev_b32_e32 v22, 16, v2
	v_and_b32_e32 v23, 0xffff0000, v2
	v_lshlrev_b32_e32 v2, 16, v3
	v_and_b32_e32 v3, 0xffff0000, v3
	v_pk_fma_f32 v[30:31], v[74:75], v[194:195], v[30:31]
	v_pk_fma_f32 v[20:21], v[20:21], v[2:3], v[32:33]
	v_lshlrev_b32_e32 v2, 16, v4
	v_and_b32_e32 v3, 0xffff0000, v4
	v_mul_f32_e32 v4, 0xbfb8aa3b, v14
	v_pk_fma_f32 v[18:19], v[18:19], v[22:23], v[30:31]
	v_exp_f32_e32 v22, v4
	v_mul_f32_e32 v4, 0xbfb8aa3b, v15
	v_exp_f32_e32 v23, v4
	v_pk_fma_f32 v[40:41], v[48:49], v[186:187], v[40:41]
	v_lshlrev_b32_e32 v4, 16, v5
	v_pk_fma_f32 v[40:41], v[56:57], v[200:201], v[40:41]
	v_add_f32_e32 v22, 1.0, v22
	v_add_f32_e32 v23, 1.0, v23
	v_and_b32_e32 v5, 0xffff0000, v5
	v_rcp_f32_e32 v22, v22
	v_rcp_f32_e32 v23, v23
	v_pk_fma_f32 v[12:13], v[12:13], v[4:5], v[40:41]
	v_mul_f32_e32 v4, 0xbfb8aa3b, v6
	v_exp_f32_e32 v4, v4
	v_mul_f32_e32 v5, 0xbfb8aa3b, v7
	v_pk_fma_f32 v[38:39], v[46:47], v[184:185], v[38:39]
	v_exp_f32_e32 v5, v5
	v_pk_fma_f32 v[38:39], v[54:55], v[198:199], v[38:39]
	v_pk_fma_f32 v[28:29], v[52:53], v[108:109], v[28:29]
	v_pk_fma_f32 v[10:11], v[10:11], v[2:3], v[38:39]
	v_pk_mul_f32 v[2:3], v[14:15], v[22:23]
	v_mul_f32_e32 v14, 0xbfb8aa3b, v17
	v_cvt_pk_bf16_f32 v2, v2, v3
	v_add_f32_e32 v3, 1.0, v4
	v_rcp_f32_e32 v4, v3
	v_add_f32_e32 v3, 1.0, v5
	v_rcp_f32_e32 v5, v3
	v_mul_f32_e32 v3, 0xbfb8aa3b, v16
	v_exp_f32_e32 v3, v3
	v_exp_f32_e32 v14, v14
	v_pk_fma_f32 v[28:29], v[84:85], v[112:113], v[28:29]
	v_lshlrev_b32_e32 v8, 16, v9
	v_and_b32_e32 v9, 0xffff0000, v9
	v_pk_fma_f32 v[8:9], v[24:25], v[8:9], v[28:29]
	v_pk_mul_f32 v[4:5], v[6:7], v[4:5]
	v_add_f32_e32 v3, 1.0, v3
	v_mul_f32_e32 v7, 0xbfb8aa3b, v8
	v_rcp_f32_e32 v6, v3
	v_add_f32_e32 v3, 1.0, v14
	v_exp_f32_e32 v14, v7
	v_mul_f32_e32 v7, 0xbfb8aa3b, v9
	v_exp_f32_e32 v15, v7
	v_rcp_f32_e32 v7, v3
	v_add_f32_e32 v3, 1.0, v14
	v_rcp_f32_e32 v14, v3
	v_add_f32_e32 v3, 1.0, v15
	v_rcp_f32_e32 v15, v3
	v_cvt_pk_bf16_f32 v3, v4, v5
	v_pk_mul_f32 v[4:5], v[16:17], v[6:7]
	ds_write_b128 v160, v[98:101]
	v_cvt_pk_bf16_f32 v4, v4, v5
	v_mul_f32_e32 v5, 0xbfb8aa3b, v18
	v_pk_mul_f32 v[6:7], v[8:9], v[14:15]
	v_exp_f32_e32 v8, v5
	v_mul_f32_e32 v5, 0xbfb8aa3b, v19
	v_exp_f32_e32 v9, v5
	v_cvt_pk_bf16_f32 v5, v6, v7
	v_add_f32_e32 v6, 1.0, v8
	v_rcp_f32_e32 v6, v6
	v_add_f32_e32 v7, 1.0, v9
	v_mul_f32_e32 v8, 0xbfb8aa3b, v20
	v_mul_f32_e32 v9, 0xbfb8aa3b, v21
	v_rcp_f32_e32 v7, v7
	v_exp_f32_e32 v8, v8
	v_exp_f32_e32 v9, v9
	global_store_dwordx4 v[168:169], v[2:5], off offset:1024
	v_pk_mul_f32 v[6:7], v[18:19], v[6:7]
	v_add_f32_e32 v8, 1.0, v8
	v_add_f32_e32 v9, 1.0, v9
	v_pk_mul_f32 v[6:7], v[6:7], s[38:39] op_sel_hi:[1,0]
	v_rcp_f32_e32 v8, v8
	v_rcp_f32_e32 v9, v9
	v_cvt_pk_bf16_f32 v6, v6, v7
	v_mul_f32_e32 v7, 0xbfb8aa3b, v10
	v_exp_f32_e32 v14, v7
	v_mul_f32_e32 v7, 0xbfb8aa3b, v11
	v_exp_f32_e32 v15, v7
	v_pk_mul_f32 v[8:9], v[20:21], v[8:9]
	v_lshl_add_u64 v[152:153], v[152:153], 0, s[42:43]
	v_pk_mul_f32 v[8:9], v[8:9], s[38:39] op_sel_hi:[1,0]
	s_nop 0
	v_cvt_pk_bf16_f32 v7, v8, v9
	v_add_f32_e32 v8, 1.0, v14
	v_add_f32_e32 v9, 1.0, v15
	v_mul_f32_e32 v14, 0xbfb8aa3b, v12
	v_mul_f32_e32 v15, 0xbfb8aa3b, v13
	v_exp_f32_e32 v14, v14
	v_exp_f32_e32 v15, v15
	v_rcp_f32_e32 v8, v8
	v_rcp_f32_e32 v9, v9
	v_add_f32_e32 v14, 1.0, v14
	v_add_f32_e32 v15, 1.0, v15
	v_rcp_f32_e32 v14, v14
	v_rcp_f32_e32 v15, v15
	v_pk_mul_f32 v[8:9], v[10:11], v[8:9]
	v_pk_mul_f32 v[10:11], v[12:13], v[14:15]
	v_pk_mul_f32 v[8:9], v[8:9], s[38:39] op_sel_hi:[1,0]
	v_pk_mul_f32 v[10:11], v[10:11], s[38:39] op_sel_hi:[1,0]
	v_cvt_pk_bf16_f32 v8, v8, v9
	v_cvt_pk_bf16_f32 v9, v10, v11
	ds_write_b128 v161, v[6:9]
	s_waitcnt lgkmcnt(0)
	s_barrier
	ds_read_u16 v6, v162
	ds_read_u16 v2, v162 offset:272
	ds_read_u16 v20, v162 offset:544
	ds_read_u16 v21, v162 offset:816
	ds_read_u16 v22, v162 offset:1088
	ds_read_u16 v23, v162 offset:1360
	ds_read_u16 v24, v162 offset:1632
	ds_read_u16 v25, v162 offset:1904
	s_waitcnt lgkmcnt(6)
	v_lshlrev_b32_e32 v19, 16, v2
	ds_read_b128 v[2:5], v125 offset:34816
	v_lshlrev_b32_e32 v18, 16, v6
	ds_read_b128 v[6:9], v125 offset:34832
	ds_read_b128 v[10:13], v125 offset:34848
	ds_read_b128 v[14:17], v125 offset:34864
	s_waitcnt lgkmcnt(8)
	v_lshlrev_b32_e32 v21, 16, v21
	v_lshlrev_b32_e32 v20, 16, v20
	s_waitcnt lgkmcnt(3)
	v_pk_mul_f32 v[2:3], v[2:3], v[18:19]
	v_pk_mul_f32 v[4:5], v[4:5], v[20:21]
	v_cvt_pk_bf16_f32 v2, v2, v3
	ds_read_u16 v3, v162 offset:17408
	ds_read_u16 v18, v162 offset:17680
	ds_read_u16 v19, v162 offset:17952
	ds_read_u16 v26, v162 offset:18224
	ds_read_u16 v27, v162 offset:18496
	ds_read_u16 v28, v162 offset:18768
	ds_read_u16 v29, v162 offset:19040
	ds_read_u16 v30, v162 offset:19312
	s_waitcnt lgkmcnt(6)
	v_lshl_or_b32 v18, v18, 16, v3
	v_cvt_pk_bf16_f32 v3, v4, v5
	v_lshlrev_b32_e32 v5, 16, v23
	v_lshlrev_b32_e32 v4, 16, v22
	v_pk_mul_f32 v[4:5], v[6:7], v[4:5]
	v_lshlrev_b32_e32 v7, 16, v25
	v_lshlrev_b32_e32 v6, 16, v24
	v_pk_mul_f32 v[6:7], v[8:9], v[6:7]
	v_cvt_pk_bf16_f32 v4, v4, v5
	v_cvt_pk_bf16_f32 v5, v6, v7
	ds_read_u16 v6, v162 offset:2176
	ds_read_u16 v7, v162 offset:2448
	ds_read_u16 v8, v162 offset:2720
	ds_read_u16 v9, v162 offset:2992
	ds_read_u16 v22, v162 offset:3264
	ds_read_u16 v23, v162 offset:3536
	ds_read_u16 v24, v162 offset:3808
	ds_read_u16 v25, v162 offset:4080
	s_waitcnt lgkmcnt(6)
	v_lshlrev_b32_e32 v7, 16, v7
	v_lshlrev_b32_e32 v6, 16, v6
	v_pk_mul_f32 v[6:7], v[10:11], v[6:7]
	s_waitcnt lgkmcnt(4)
	v_lshlrev_b32_e32 v9, 16, v9
	v_lshlrev_b32_e32 v8, 16, v8
	v_lshl_or_b32 v19, v26, 16, v19
	v_lshl_or_b32 v20, v28, 16, v27
	v_lshl_or_b32 v21, v30, 16, v29
	v_cvt_pk_bf16_f32 v6, v6, v7
	ds_read_u16 v7, v162 offset:19584
	ds_read_u16 v10, v162 offset:19856
	ds_read_u16 v11, v162 offset:20128
	ds_read_u16 v26, v162 offset:20400
	ds_read_u16 v27, v162 offset:20672
	ds_read_u16 v28, v162 offset:20944
	ds_read_u16 v29, v162 offset:21216
	ds_read_u16 v30, v162 offset:21488
	v_pk_mul_f32 v[8:9], v[12:13], v[8:9]
	s_waitcnt lgkmcnt(6)
	v_lshl_or_b32 v10, v10, 16, v7
	v_cvt_pk_bf16_f32 v7, v8, v9
	v_lshlrev_b32_e32 v9, 16, v23
	v_lshlrev_b32_e32 v8, 16, v22
	v_pk_mul_f32 v[8:9], v[14:15], v[8:9]
	v_lshlrev_b32_e32 v15, 16, v25
	v_lshlrev_b32_e32 v14, 16, v24
	v_pk_mul_f32 v[14:15], v[16:17], v[14:15]
	v_cvt_pk_bf16_f32 v8, v8, v9
	v_cvt_pk_bf16_f32 v9, v14, v15
	v_lshl_add_u64 v[14:15], s[26:27], 0, v[144:145]
	v_add_co_u32_e32 v16, vcc, s69, v14
	s_add_i32 s39, s39, 64
	s_nop 0
	v_addc_co_u32_e32 v17, vcc, 0, v15, vcc
	s_add_u32 s50, s50, 8
	global_store_dwordx4 v[16:17], v[2:5], off
	global_store_dwordx4 v[16:17], v[6:9], off offset:16
	s_addc_u32 s51, s51, 0
	v_add_co_u32_e32 v2, vcc, s70, v14
	v_lshl_add_u64 v[144:145], v[144:145], 0, s[40:41]
	s_nop 0
	v_addc_co_u32_e32 v3, vcc, 0, v15, vcc
	s_cmpk_eq_i32 s39, 0x100
	s_waitcnt lgkmcnt(4)
	v_lshl_or_b32 v11, v26, 16, v11
	s_waitcnt lgkmcnt(2)
	v_lshl_or_b32 v12, v28, 16, v27
	s_waitcnt lgkmcnt(0)
	v_lshl_or_b32 v13, v30, 16, v29
	global_store_dwordx4 v[2:3], v[18:21], off
	global_store_dwordx4 v[2:3], v[10:13], off offset:16
	s_barrier
	s_cbranch_scc1 .LBB0_863
.LBB0_849:
.LBB0_853:
	v_add_u32_e32 v10, s39, v157
	v_add_u32_e32 v126, -3, v10
	v_cmp_lt_i32_e32 vcc, -1, v126
	v_mov_b32_e32 v38, 0
	v_mov_b32_e32 v102, 0
	v_mov_b32_e32 v103, 0
	v_mov_b32_e32 v104, 0
	v_mov_b32_e32 v105, 0
	v_mov_b32_e32 v118, 0
	v_mov_b32_e32 v119, 0
	v_mov_b32_e32 v120, 0
	v_mov_b32_e32 v121, 0
	s_and_saveexec_b64 s[60:61], vcc
	s_cbranch_execz .LBB0_855
	v_lshl_add_u64 v[2:3], s[20:21], 0, v[126:127]
	v_lshlrev_b64 v[2:3], 10, v[2:3]
	v_lshl_or_b32 v2, v124, 1, v2
	s_waitcnt lgkmcnt(1)
	v_lshl_add_u64 v[4:5], s[28:29], 0, v[2:3]
	v_lshl_add_u64 v[2:3], s[30:31], 0, v[2:3]
	global_load_dwordx4 v[118:121], v[4:5], off
	global_load_dwordx4 v[102:105], v[2:3], off

.LBB0_1219:
	s_or_b64 exec, exec, s[22:23]
	v_mov_b32_e32 v110, s28
	ds_read_b128 v[134:137], v133
	ds_read_b64 v[110:111], v110
	ds_read_b128 v[138:141], v133 offset:64
	ds_read_b128 v[146:149], v133 offset:2304
	s_waitcnt vmcnt(16) lgkmcnt(3)
	v_mfma_f32_16x16x32_bf16 v[142:145], v[2:5], v[134:137], 0
	s_waitcnt lgkmcnt(2)
	v_add_f32_e32 v110, v115, v110
	v_max_f32_e32 v111, v111, v111
	v_max_f32_e32 v134, v110, v111
	v_sub_f32_e32 v110, v110, v134
	v_mul_f32_e32 v110, 0x3fb8aa3b, v110
	v_exp_f32_e32 v110, v110
	v_mul_f32_e32 v111, 0xbfb8aa3b, v134
	s_waitcnt vmcnt(15) lgkmcnt(1)
	v_mfma_f32_16x16x32_bf16 v[136:139], v[6:9], v[138:141], v[142:145]
	v_mul_f32_e64 v114, v126, v110
	v_mul_f32_e64 v115, v127, v110
	v_pk_mul_f32 v[124:125], v[124:125], v[110:111] op_sel_hi:[1,0]
	ds_read_b128 v[140:143], v133 offset:2368
	s_waitcnt lgkmcnt(1)
	v_mfma_f32_16x16x32_bf16 v[144:147], v[2:5], v[146:149], 0
	v_exp_f32_e32 v148, v111
	s_nop 0
	v_pk_fma_f32 v[124:125], v[138:139], v[148:149], v[124:125] op_sel_hi:[1,0,1]
	v_pk_fma_f32 v[128:129], v[136:137], v[148:149], v[114:115] op_sel_hi:[1,0,1]
	v_mfma_f32_16x16x32_bf16 v[136:139], v[2:5], v[86:89], 0
	s_waitcnt lgkmcnt(0)
	v_mfma_f32_16x16x32_bf16 v[140:143], v[6:9], v[140:143], v[144:147]
	v_mfma_f32_16x16x32_bf16 v[136:139], v[6:9], v[86:89], v[136:139]
	s_nop 6
	v_mul_f32_e64 v114, v148, v142
	v_mul_f32_e64 v115, v148, v143
	v_pk_mul_f32 v[126:127], v[148:149], v[140:141] op_sel_hi:[0,1]
	v_pk_fma_f32 v[114:115], v[122:123], v[110:111], v[114:115] op_sel_hi:[1,0,1]
	v_pk_fma_f32 v[118:119], v[118:119], v[110:111], v[126:127] op_sel_hi:[1,0,1]
	v_pk_mul_f32 v[122:123], v[110:111], v[120:121] op_sel_hi:[0,1]
	v_pk_mul_f32 v[110:111], v[110:111], v[116:117] op_sel_hi:[0,1]
	v_pk_fma_f32 v[120:121], v[148:149], v[138:139], v[110:111] op_sel_hi:[0,1,1]
	v_lshl_add_u64 v[110:111], s[16:17], 0, v[104:105]
	v_pk_fma_f32 v[126:127], v[148:149], v[136:137], v[122:123] op_sel_hi:[0,1,1]
	v_cvt_pk_bf16_f32 v136, v128, v129
	v_cvt_pk_bf16_f32 v138, v118, v119
	v_cvt_pk_bf16_f32 v137, v124, v125
	v_cvt_pk_bf16_f32 v139, v114, v115
	v_add_co_u32_e32 v116, vcc, 0x9008000, v110
	v_permlane16_swap_b32_e32 v136, v138
	v_permlane16_swap_b32_e32 v137, v139
	v_addc_co_u32_e32 v117, vcc, 0, v111, vcc
	s_waitcnt lgkmcnt(0)
	s_barrier
	s_add_i32 s22, s29, 9
	s_cmp_gt_u32 s22, 56
	s_cbranch_scc1 .LBB0_1227
	v_add_co_u32_e32 v6, vcc, 0xd020000, v112
	s_nop 1
	v_addc_co_u32_e32 v7, vcc, 0, v113, vcc
	global_load_dwordx4 v[2:5], v[6:7], off
	s_nop 0
	global_load_dwordx4 v[6:9], v[6:7], off offset:64
	s_and_saveexec_b64 s[22:23], s[8:9]
	s_cbranch_execz .LBB0_1226
	v_lshl_add_u64 v[10:11], s[16:17], 0, v[106:107]
	v_add_co_u32_e32 v10, vcc, 0xe020000, v10
	s_nop 1
	v_addc_co_u32_e32 v11, vcc, 0, v11, vcc
	global_load_dwordx4 v[10:13], v[10:11], off

.LBB0_1227:
	s_and_saveexec_b64 s[22:23], s[8:9]
	s_cbranch_execz .LBB0_1229
	s_waitcnt vmcnt(19)
	ds_write_b128 v131, v[34:37] offset:9216
.LBB0_1229:
	s_or_b64 exec, exec, s[22:23]
	global_store_dwordx4 v[116:117], v[136:139], off offset:256
	s_and_saveexec_b64 s[98:99], s[10:11]
	s_cbranch_execz .LBB0_1221
	v_lshl_add_u64 v[122:123], s[16:17], 0, v[102:103]
	v_add_co_u32_e32 v122, vcc, 0x9010000, v122
	v_cvt_pk_bf16_f32 v116, v126, v127
	v_cvt_pk_bf16_f32 v117, v120, v121
	v_addc_co_u32_e32 v123, vcc, 0, v123, vcc
	global_store_dwordx2 v[122:123], v[116:117], off offset:256
.LBB0_1221:
	s_or_b64 exec, exec, s[98:99]
	s_and_saveexec_b64 s[98:99], s[18:19]
	s_cbranch_execz .LBB0_1223
	s_add_u32 s100, s16, s12
	s_addc_u32 s101, s17, s13
	global_store_dword v130, v134, s[100:101] offset:4
.LBB0_1223:
	s_or_b64 exec, exec, s[98:99]
	v_mov_b32_e32 v116, s28
	ds_read_b128 v[136:139], v133 offset:4608
	ds_read_b64 v[116:117], v116 offset:8
	ds_read_b128 v[140:143], v133 offset:4672
	ds_read_b128 v[144:147], v133 offset:6912
	s_waitcnt vmcnt(17) lgkmcnt(3)
	v_mfma_f32_16x16x32_bf16 v[136:139], v[14:17], v[136:139], 0
	s_waitcnt lgkmcnt(2)
	v_add_f32_e32 v116, v134, v116
	v_max_f32_e32 v117, v117, v117
	v_max_f32_e32 v134, v116, v117
	v_sub_f32_e32 v116, v116, v134
	v_mul_f32_e32 v116, 0x3fb8aa3b, v116
	v_exp_f32_e32 v148, v116
	v_mul_f32_e32 v116, 0xbfb8aa3b, v134
	s_waitcnt vmcnt(16) lgkmcnt(1)
	v_mfma_f32_16x16x32_bf16 v[136:139], v[18:21], v[140:143], v[136:139]
	v_exp_f32_e32 v150, v116
	ds_read_b128 v[140:143], v133 offset:6976
	v_pk_mul_f32 v[116:117], v[128:129], v[148:149] op_sel_hi:[1,0]
	s_waitcnt lgkmcnt(1)
	v_mfma_f32_16x16x32_bf16 v[144:147], v[14:17], v[144:147], 0
	v_mul_f32_e64 v122, v124, v148
	v_mul_f32_e64 v123, v125, v148
	s_nop 0
	v_pk_fma_f32 v[128:129], v[136:137], v[150:151], v[116:117] op_sel_hi:[1,0,1]
	v_pk_fma_f32 v[124:125], v[138:139], v[150:151], v[122:123] op_sel_hi:[1,0,1]
	v_mfma_f32_16x16x32_bf16 v[136:139], v[14:17], v[86:89], 0
	s_waitcnt lgkmcnt(0)
	v_mfma_f32_16x16x32_bf16 v[140:143], v[18:21], v[140:143], v[144:147]
	v_mfma_f32_16x16x32_bf16 v[136:139], v[18:21], v[86:89], v[136:139]
	s_nop 6
	v_mul_f32_e64 v116, v150, v142
	v_mul_f32_e64 v117, v150, v143
	v_pk_mul_f32 v[122:123], v[150:151], v[140:141] op_sel_hi:[0,1]
	v_pk_fma_f32 v[116:117], v[114:115], v[148:149], v[116:117] op_sel_hi:[1,0,1]
	v_pk_fma_f32 v[122:123], v[118:119], v[148:149], v[122:123] op_sel_hi:[1,0,1]
	v_pk_mul_f32 v[114:115], v[150:151], v[138:139] op_sel_hi:[0,1]
	v_pk_mul_f32 v[118:119], v[150:151], v[136:137] op_sel_hi:[0,1]
	v_pk_fma_f32 v[114:115], v[120:121], v[148:149], v[114:115] op_sel_hi:[1,0,1]
	v_cvt_pk_bf16_f32 v136, v128, v129
	v_cvt_pk_bf16_f32 v138, v122, v123
	v_cvt_pk_bf16_f32 v137, v124, v125
	v_cvt_pk_bf16_f32 v139, v116, v117
	v_add_co_u32_e32 v120, vcc, 0x9010000, v110
	v_pk_fma_f32 v[118:119], v[126:127], v[148:149], v[118:119] op_sel_hi:[1,0,1]
	v_permlane16_swap_b32_e32 v136, v138
	v_permlane16_swap_b32_e32 v137, v139
	v_addc_co_u32_e32 v121, vcc, 0, v111, vcc
	s_waitcnt lgkmcnt(0)
	s_barrier
	s_add_i32 s22, s29, 10
	s_cmp_gt_u32 s22, 56
	s_cbranch_scc1 .LBB0_1237
	v_add_co_u32_e32 v18, vcc, 0xd024000, v112
	s_nop 1
	v_addc_co_u32_e32 v19, vcc, 0, v113, vcc
	global_load_dwordx4 v[14:17], v[18:19], off
	s_nop 0
	global_load_dwordx4 v[18:21], v[18:19], off offset:64
	s_and_saveexec_b64 s[22:23], s[8:9]
	s_cbranch_execz .LBB0_1236
	v_lshl_add_u64 v[22:23], s[16:17], 0, v[106:107]
	v_add_co_u32_e32 v22, vcc, 0xe024000, v22
	s_nop 1
	v_addc_co_u32_e32 v23, vcc, 0, v23, vcc
	global_load_dwordx4 v[22:25], v[22:23], off

.LBB0_1237:
	s_and_saveexec_b64 s[22:23], s[8:9]
	s_cbranch_execz .LBB0_1239
	s_waitcnt vmcnt(20)
	ds_write_b128 v131, v[46:49] offset:13824
.LBB0_1239:
	s_or_b64 exec, exec, s[22:23]
	global_store_dwordx4 v[120:121], v[136:139], off offset:512
	s_and_saveexec_b64 s[98:99], s[10:11]
	s_cbranch_execz .LBB0_1231
	v_lshl_add_u64 v[126:127], s[16:17], 0, v[102:103]
	v_add_co_u32_e32 v126, vcc, 0x9018000, v126
	v_cvt_pk_bf16_f32 v120, v118, v119
	v_cvt_pk_bf16_f32 v121, v114, v115
	v_addc_co_u32_e32 v127, vcc, 0, v127, vcc
	global_store_dwordx2 v[126:127], v[120:121], off offset:512
.LBB0_1231:
	s_or_b64 exec, exec, s[98:99]
	s_and_saveexec_b64 s[98:99], s[18:19]
	s_cbranch_execz .LBB0_1233
	s_add_u32 s100, s16, s12
	s_addc_u32 s101, s17, s13
	global_store_dword v130, v134, s[100:101] offset:8
.LBB0_1233:
	s_or_b64 exec, exec, s[98:99]
	v_mov_b32_e32 v120, s28
	ds_read_b128 v[136:139], v133 offset:9216
	ds_read_b64 v[120:121], v120 offset:16
	ds_read_b128 v[140:143], v133 offset:9280
	ds_read_b128 v[144:147], v133 offset:11520
	s_waitcnt vmcnt(18) lgkmcnt(3)
	v_mfma_f32_16x16x32_bf16 v[136:139], v[26:29], v[136:139], 0
	s_waitcnt lgkmcnt(2)
	v_add_f32_e32 v120, v134, v120
	v_max_f32_e32 v121, v121, v121
	v_max_f32_e32 v134, v120, v121
	v_sub_f32_e32 v120, v120, v134
	v_mul_f32_e32 v120, 0x3fb8aa3b, v120
	v_exp_f32_e32 v148, v120
	v_mul_f32_e32 v120, 0xbfb8aa3b, v134
	s_waitcnt vmcnt(17) lgkmcnt(1)
	v_mfma_f32_16x16x32_bf16 v[136:139], v[30:33], v[140:143], v[136:139]
	v_exp_f32_e32 v150, v120
	ds_read_b128 v[140:143], v133 offset:11584
	v_pk_mul_f32 v[120:121], v[128:129], v[148:149] op_sel_hi:[1,0]
	s_waitcnt lgkmcnt(1)
	v_mfma_f32_16x16x32_bf16 v[144:147], v[26:29], v[144:147], 0
	v_mul_f32_e64 v124, v124, v148
	v_mul_f32_e64 v125, v125, v148
	s_nop 0
	v_pk_fma_f32 v[126:127], v[136:137], v[150:151], v[120:121] op_sel_hi:[1,0,1]
	v_pk_fma_f32 v[124:125], v[138:139], v[150:151], v[124:125] op_sel_hi:[1,0,1]
	v_mfma_f32_16x16x32_bf16 v[136:139], v[26:29], v[86:89], 0
	s_waitcnt lgkmcnt(0)
	v_mfma_f32_16x16x32_bf16 v[140:143], v[30:33], v[140:143], v[144:147]
	v_mfma_f32_16x16x32_bf16 v[136:139], v[30:33], v[86:89], v[136:139]
	s_nop 6
	v_mul_f32_e64 v120, v150, v142
	v_mul_f32_e64 v121, v150, v143
	v_pk_mul_f32 v[128:129], v[150:151], v[140:141] op_sel_hi:[0,1]
	v_pk_fma_f32 v[116:117], v[116:117], v[148:149], v[120:121] op_sel_hi:[1,0,1]
	v_pk_fma_f32 v[120:121], v[122:123], v[148:149], v[128:129] op_sel_hi:[1,0,1]
	v_pk_mul_f32 v[122:123], v[150:151], v[138:139] op_sel_hi:[0,1]
	v_pk_mul_f32 v[128:129], v[150:151], v[136:137] op_sel_hi:[0,1]
	v_pk_fma_f32 v[114:115], v[114:115], v[148:149], v[122:123] op_sel_hi:[1,0,1]
	v_cvt_pk_bf16_f32 v136, v126, v127
	v_cvt_pk_bf16_f32 v138, v120, v121
	v_cvt_pk_bf16_f32 v137, v124, v125
	v_cvt_pk_bf16_f32 v139, v116, v117
	v_add_co_u32_e32 v122, vcc, 0x9018000, v110
	v_pk_fma_f32 v[118:119], v[118:119], v[148:149], v[128:129] op_sel_hi:[1,0,1]
	v_permlane16_swap_b32_e32 v136, v138
	v_permlane16_swap_b32_e32 v137, v139
	v_addc_co_u32_e32 v123, vcc, 0, v111, vcc
	s_waitcnt lgkmcnt(0)
	s_barrier
	s_add_i32 s22, s29, 11
	s_cmp_gt_u32 s22, 56
	s_cbranch_scc1 .LBB0_1247
	v_add_co_u32_e32 v30, vcc, 0xd028000, v112
	s_nop 1
	v_addc_co_u32_e32 v31, vcc, 0, v113, vcc
	global_load_dwordx4 v[26:29], v[30:31], off
	s_nop 0
	global_load_dwordx4 v[30:33], v[30:31], off offset:64
	s_and_saveexec_b64 s[22:23], s[8:9]
	s_cbranch_execz .LBB0_1246
	v_lshl_add_u64 v[34:35], s[16:17], 0, v[106:107]
	v_add_co_u32_e32 v34, vcc, 0xe028000, v34
	s_nop 1
	v_addc_co_u32_e32 v35, vcc, 0, v35, vcc
	global_load_dwordx4 v[34:37], v[34:35], off

.LBB0_1247:
	s_and_saveexec_b64 s[22:23], s[8:9]
	s_cbranch_execz .LBB0_1249
	s_waitcnt vmcnt(21)
	ds_write_b128 v131, v[58:61] offset:18432
.LBB0_1249:
	s_or_b64 exec, exec, s[22:23]
	global_store_dwordx4 v[122:123], v[136:139], off offset:768
	s_and_saveexec_b64 s[98:99], s[10:11]
	s_cbranch_execz .LBB0_1241
	v_lshl_add_u64 v[128:129], s[16:17], 0, v[102:103]
	v_add_co_u32_e32 v128, vcc, 0x9020000, v128
	v_cvt_pk_bf16_f32 v122, v118, v119
	v_cvt_pk_bf16_f32 v123, v114, v115
	v_addc_co_u32_e32 v129, vcc, 0, v129, vcc
	global_store_dwordx2 v[128:129], v[122:123], off offset:768
.LBB0_1241:
	s_or_b64 exec, exec, s[98:99]
	s_and_saveexec_b64 s[98:99], s[18:19]
	s_cbranch_execz .LBB0_1243
	s_add_u32 s100, s16, s12
	s_addc_u32 s101, s17, s13
	global_store_dword v130, v134, s[100:101] offset:12
.LBB0_1243:
	s_or_b64 exec, exec, s[98:99]
	v_mov_b32_e32 v122, s28
	ds_read_b128 v[136:139], v133 offset:13824
	ds_read_b64 v[122:123], v122 offset:24
	ds_read_b128 v[140:143], v133 offset:13888
	ds_read_b128 v[144:147], v133 offset:16128
	s_waitcnt vmcnt(19) lgkmcnt(3)
	v_mfma_f32_16x16x32_bf16 v[136:139], v[38:41], v[136:139], 0
	s_waitcnt lgkmcnt(2)
	v_add_f32_e32 v122, v134, v122
	v_max_f32_e32 v123, v123, v123
	v_max_f32_e32 v128, v122, v123
	v_sub_f32_e32 v122, v122, v128
	v_mul_f32_e32 v122, 0x3fb8aa3b, v122
	v_exp_f32_e32 v148, v122
	v_mul_f32_e32 v122, 0xbfb8aa3b, v128
	s_waitcnt vmcnt(18) lgkmcnt(1)
	v_mfma_f32_16x16x32_bf16 v[134:137], v[42:45], v[140:143], v[136:139]
	v_mul_f32_e64 v126, v126, v148
	v_mul_f32_e64 v127, v127, v148
	s_nop 0
	ds_read_b128 v[138:141], v133 offset:16192
	s_waitcnt lgkmcnt(1)
	v_mfma_f32_16x16x32_bf16 v[142:145], v[38:41], v[144:147], 0
	v_exp_f32_e32 v146, v122
	v_pk_mul_f32 v[122:123], v[124:125], v[148:149] op_sel_hi:[1,0]
	v_pk_fma_f32 v[124:125], v[134:135], v[146:147], v[126:127] op_sel_hi:[1,0,1]
	v_pk_fma_f32 v[122:123], v[136:137], v[146:147], v[122:123] op_sel_hi:[1,0,1]
	v_mfma_f32_16x16x32_bf16 v[134:137], v[38:41], v[86:89], 0
	s_waitcnt lgkmcnt(0)
	v_mfma_f32_16x16x32_bf16 v[138:141], v[42:45], v[138:141], v[142:145]
	v_mfma_f32_16x16x32_bf16 v[134:137], v[42:45], v[86:89], v[134:137]
	s_nop 6
	v_mul_f32_e64 v126, v146, v140
	v_mul_f32_e64 v127, v146, v141
	v_pk_mul_f32 v[138:139], v[146:147], v[138:139] op_sel_hi:[0,1]
	v_pk_fma_f32 v[116:117], v[116:117], v[148:149], v[126:127] op_sel_hi:[1,0,1]
	v_pk_fma_f32 v[120:121], v[120:121], v[148:149], v[138:139] op_sel_hi:[1,0,1]
	v_pk_mul_f32 v[126:127], v[146:147], v[136:137] op_sel_hi:[0,1]
	v_pk_mul_f32 v[134:135], v[146:147], v[134:135] op_sel_hi:[0,1]
	v_pk_fma_f32 v[114:115], v[114:115], v[148:149], v[126:127] op_sel_hi:[1,0,1]
	v_pk_fma_f32 v[118:119], v[118:119], v[148:149], v[134:135] op_sel_hi:[1,0,1]
	v_cvt_pk_bf16_f32 v134, v124, v125
	v_cvt_pk_bf16_f32 v136, v120, v121
	v_cvt_pk_bf16_f32 v135, v122, v123
	v_cvt_pk_bf16_f32 v137, v116, v117
	v_add_co_u32_e32 v126, vcc, 0x9020000, v110
	v_permlane16_swap_b32_e32 v134, v136
	v_permlane16_swap_b32_e32 v135, v137
	v_addc_co_u32_e32 v127, vcc, 0, v111, vcc
	s_waitcnt lgkmcnt(0)
	s_barrier
	s_add_i32 s22, s29, 12
	s_cmp_gt_u32 s22, 56
	s_cbranch_scc1 .LBB0_1257
	v_add_co_u32_e32 v42, vcc, 0xd02c000, v112
	s_nop 1
	v_addc_co_u32_e32 v43, vcc, 0, v113, vcc
	global_load_dwordx4 v[38:41], v[42:43], off
	s_nop 0
	global_load_dwordx4 v[42:45], v[42:43], off offset:64
	s_and_saveexec_b64 s[22:23], s[8:9]
	s_cbranch_execz .LBB0_1256
	v_lshl_add_u64 v[46:47], s[16:17], 0, v[106:107]
	v_add_co_u32_e32 v46, vcc, 0xe02c000, v46
	s_nop 1
	v_addc_co_u32_e32 v47, vcc, 0, v47, vcc
	global_load_dwordx4 v[46:49], v[46:47], off

.LBB0_1257:
	s_and_saveexec_b64 s[22:23], s[8:9]
	s_cbranch_execz .LBB0_1259
	s_waitcnt vmcnt(22)
	ds_write_b128 v131, v[70:73] offset:23040
.LBB0_1259:
	s_or_b64 exec, exec, s[22:23]
	global_store_dwordx4 v[126:127], v[134:137], off offset:1024
	s_and_saveexec_b64 s[98:99], s[10:11]
	s_cbranch_execz .LBB0_1251
	v_lshl_add_u64 v[134:135], s[16:17], 0, v[102:103]
	v_add_co_u32_e32 v134, vcc, 0x9028000, v134
	v_cvt_pk_bf16_f32 v126, v118, v119
	v_cvt_pk_bf16_f32 v127, v114, v115
	v_addc_co_u32_e32 v135, vcc, 0, v135, vcc
	global_store_dwordx2 v[134:135], v[126:127], off offset:1024
.LBB0_1251:
	s_or_b64 exec, exec, s[98:99]
	s_and_saveexec_b64 s[98:99], s[18:19]
	s_cbranch_execz .LBB0_1253
	s_add_u32 s100, s16, s12
	s_addc_u32 s101, s17, s13
	global_store_dword v130, v128, s[100:101] offset:16
.LBB0_1253:
	s_or_b64 exec, exec, s[98:99]
	v_mov_b32_e32 v126, s28
	ds_read_b128 v[134:137], v133 offset:18432
	ds_read_b64 v[126:127], v126 offset:32
	ds_read_b128 v[138:141], v133 offset:18496
	ds_read_b128 v[142:145], v133 offset:20736
	s_waitcnt vmcnt(20) lgkmcnt(3)
	v_mfma_f32_16x16x32_bf16 v[134:137], v[50:53], v[134:137], 0
	s_waitcnt lgkmcnt(2)
	v_add_f32_e32 v128, v128, v126
	v_max_f32_e32 v126, v127, v127
	v_max_f32_e32 v126, v128, v126
	v_sub_f32_e32 v127, v128, v126
	v_mul_f32_e32 v127, 0x3fb8aa3b, v127
	v_exp_f32_e32 v128, v127
	v_mul_f32_e32 v127, 0xbfb8aa3b, v126
	s_waitcnt vmcnt(19) lgkmcnt(1)
	v_mfma_f32_16x16x32_bf16 v[134:137], v[54:57], v[138:141], v[134:137]
	v_exp_f32_e32 v146, v127
	ds_read_b128 v[138:141], v133 offset:20800
	v_pk_mul_f32 v[124:125], v[124:125], v[128:129] op_sel_hi:[1,0]
	s_waitcnt lgkmcnt(1)
	v_mfma_f32_16x16x32_bf16 v[142:145], v[50:53], v[142:145], 0
	v_mul_f32_e64 v122, v122, v128
	v_mul_f32_e64 v123, v123, v128
	s_nop 0
	v_pk_fma_f32 v[124:125], v[134:135], v[146:147], v[124:125] op_sel_hi:[1,0,1]
	v_pk_fma_f32 v[122:123], v[136:137], v[146:147], v[122:123] op_sel_hi:[1,0,1]
	v_mfma_f32_16x16x32_bf16 v[134:137], v[50:53], v[86:89], 0
	s_waitcnt lgkmcnt(0)
	v_mfma_f32_16x16x32_bf16 v[138:141], v[54:57], v[138:141], v[142:145]
	v_mfma_f32_16x16x32_bf16 v[134:137], v[54:57], v[86:89], v[134:137]
	s_nop 6
	v_mul_f32_e64 v140, v146, v140
	v_mul_f32_e64 v141, v146, v141
	v_pk_mul_f32 v[138:139], v[146:147], v[138:139] op_sel_hi:[0,1]
	v_pk_fma_f32 v[116:117], v[116:117], v[128:129], v[140:141] op_sel_hi:[1,0,1]
	v_pk_fma_f32 v[120:121], v[120:121], v[128:129], v[138:139] op_sel_hi:[1,0,1]
	v_pk_mul_f32 v[136:137], v[146:147], v[136:137] op_sel_hi:[0,1]
	v_pk_mul_f32 v[134:135], v[146:147], v[134:135] op_sel_hi:[0,1]
	v_pk_fma_f32 v[114:115], v[114:115], v[128:129], v[136:137] op_sel_hi:[1,0,1]
	v_pk_fma_f32 v[118:119], v[118:119], v[128:129], v[134:135] op_sel_hi:[1,0,1]
	v_cvt_pk_bf16_f32 v134, v124, v125
	v_cvt_pk_bf16_f32 v136, v120, v121
	v_cvt_pk_bf16_f32 v135, v122, v123
	v_cvt_pk_bf16_f32 v137, v116, v117
	v_add_co_u32_e32 v128, vcc, 0x9028000, v110
	v_permlane16_swap_b32_e32 v134, v136
	v_permlane16_swap_b32_e32 v135, v137
	v_addc_co_u32_e32 v129, vcc, 0, v111, vcc
	s_waitcnt lgkmcnt(0)
	s_barrier
	s_add_i32 s22, s29, 13
	s_cmp_gt_u32 s22, 56
	s_cbranch_scc1 .LBB0_1267
	v_add_co_u32_e32 v54, vcc, 0xd030000, v112
	s_nop 1
	v_addc_co_u32_e32 v55, vcc, 0, v113, vcc
	global_load_dwordx4 v[50:53], v[54:55], off
	s_nop 0
	global_load_dwordx4 v[54:57], v[54:55], off offset:64
	s_and_saveexec_b64 s[22:23], s[8:9]
	s_cbranch_execz .LBB0_1266
	v_lshl_add_u64 v[58:59], s[16:17], 0, v[106:107]
	v_add_co_u32_e32 v58, vcc, 0xe030000, v58
	s_nop 1
	v_addc_co_u32_e32 v59, vcc, 0, v59, vcc
	global_load_dwordx4 v[58:61], v[58:59], off

.LBB0_1267:
	s_and_saveexec_b64 s[22:23], s[8:9]
	s_cbranch_execz .LBB0_1269
	s_waitcnt vmcnt(23)
	ds_write_b128 v131, v[82:85] offset:27648
.LBB0_1269:
	s_or_b64 exec, exec, s[22:23]
	global_store_dwordx4 v[128:129], v[134:137], off offset:1280
	s_and_saveexec_b64 s[98:99], s[10:11]
	s_cbranch_execz .LBB0_1261
	v_lshl_add_u64 v[134:135], s[16:17], 0, v[102:103]
	v_add_co_u32_e32 v134, vcc, 0x9030000, v134
	v_cvt_pk_bf16_f32 v128, v118, v119
	v_cvt_pk_bf16_f32 v129, v114, v115
	v_addc_co_u32_e32 v135, vcc, 0, v135, vcc
	global_store_dwordx2 v[134:135], v[128:129], off offset:1280
.LBB0_1261:
	s_or_b64 exec, exec, s[98:99]
	s_and_saveexec_b64 s[98:99], s[18:19]
	s_cbranch_execz .LBB0_1263
	s_add_u32 s100, s16, s12
	s_addc_u32 s101, s17, s13
	global_store_dword v130, v126, s[100:101] offset:20
.LBB0_1263:
	s_or_b64 exec, exec, s[98:99]
	v_mov_b32_e32 v127, s28
	ds_read_b128 v[134:137], v133 offset:23040
	ds_read_b64 v[128:129], v127 offset:40
	ds_read_b128 v[138:141], v133 offset:23104
	ds_read_b128 v[142:145], v133 offset:25344
	s_waitcnt vmcnt(21) lgkmcnt(3)
	v_mfma_f32_16x16x32_bf16 v[134:137], v[62:65], v[134:137], 0
	s_waitcnt lgkmcnt(2)
	v_add_f32_e32 v126, v126, v128
	v_max_f32_e32 v127, v129, v129
	v_max_f32_e32 v128, v126, v127
	v_sub_f32_e32 v126, v126, v128
	v_mul_f32_e32 v126, 0x3fb8aa3b, v126
	v_exp_f32_e32 v146, v126
	v_mul_f32_e32 v126, 0xbfb8aa3b, v128
	s_waitcnt vmcnt(20) lgkmcnt(1)
	v_mfma_f32_16x16x32_bf16 v[134:137], v[66:69], v[138:141], v[134:137]
	v_exp_f32_e32 v148, v126
	ds_read_b128 v[138:141], v133 offset:25408
	v_pk_mul_f32 v[124:125], v[124:125], v[146:147] op_sel_hi:[1,0]
	s_waitcnt lgkmcnt(1)
	v_mfma_f32_16x16x32_bf16 v[142:145], v[62:65], v[142:145], 0
	v_mul_f32_e64 v122, v122, v146
	v_mul_f32_e64 v123, v123, v146
	s_nop 0
	v_pk_fma_f32 v[126:127], v[134:135], v[148:149], v[124:125] op_sel_hi:[1,0,1]
	v_pk_fma_f32 v[122:123], v[136:137], v[148:149], v[122:123] op_sel_hi:[1,0,1]
	v_mfma_f32_16x16x32_bf16 v[134:137], v[62:65], v[86:89], 0
	s_waitcnt lgkmcnt(0)
	v_mfma_f32_16x16x32_bf16 v[138:141], v[66:69], v[138:141], v[142:145]
	v_mfma_f32_16x16x32_bf16 v[134:137], v[66:69], v[86:89], v[134:137]
	s_nop 6
	v_mul_f32_e64 v124, v148, v140
	v_mul_f32_e64 v125, v148, v141
	v_pk_mul_f32 v[138:139], v[148:149], v[138:139] op_sel_hi:[0,1]
	v_pk_fma_f32 v[116:117], v[116:117], v[146:147], v[124:125] op_sel_hi:[1,0,1]
	v_pk_fma_f32 v[124:125], v[120:121], v[146:147], v[138:139] op_sel_hi:[1,0,1]
	v_pk_mul_f32 v[120:121], v[148:149], v[136:137] op_sel_hi:[0,1]
	v_pk_mul_f32 v[134:135], v[148:149], v[134:135] op_sel_hi:[0,1]
	v_pk_fma_f32 v[114:115], v[114:115], v[146:147], v[120:121] op_sel_hi:[1,0,1]
	v_pk_fma_f32 v[120:121], v[118:119], v[146:147], v[134:135] op_sel_hi:[1,0,1]
	v_cvt_pk_bf16_f32 v134, v126, v127
	v_cvt_pk_bf16_f32 v136, v124, v125
	v_cvt_pk_bf16_f32 v135, v122, v123
	v_cvt_pk_bf16_f32 v137, v116, v117
	v_add_co_u32_e32 v118, vcc, 0x9030000, v110
	v_permlane16_swap_b32_e32 v134, v136
	v_permlane16_swap_b32_e32 v135, v137
	v_addc_co_u32_e32 v119, vcc, 0, v111, vcc
	s_waitcnt lgkmcnt(0)
	s_barrier
	s_add_i32 s22, s29, 14
	s_cmp_gt_u32 s22, 56
	s_cbranch_scc1 .LBB0_1277
	v_add_co_u32_e32 v66, vcc, 0xd034000, v112
	s_nop 1
	v_addc_co_u32_e32 v67, vcc, 0, v113, vcc
	global_load_dwordx4 v[62:65], v[66:67], off
	s_nop 0
	global_load_dwordx4 v[66:69], v[66:67], off offset:64
	s_and_saveexec_b64 s[22:23], s[8:9]
	s_cbranch_execz .LBB0_1276
	v_lshl_add_u64 v[70:71], s[16:17], 0, v[106:107]
	v_add_co_u32_e32 v70, vcc, 0xe034000, v70
	s_nop 1
	v_addc_co_u32_e32 v71, vcc, 0, v71, vcc
	global_load_dwordx4 v[70:73], v[70:71], off

.LBB0_1277:
	s_and_saveexec_b64 s[22:23], s[8:9]
	s_cbranch_execz .LBB0_1279
	s_cmp_lg_u32 s29, 48
	s_cbranch_scc1 .Lch_rlx_18
	s_waitcnt vmcnt(5)
.Lch_rlx_18:
	s_waitcnt vmcnt(23)
	ds_write_b128 v131, v[90:93] offset:32256
.LBB0_1279:
	s_or_b64 exec, exec, s[22:23]
	global_store_dwordx4 v[118:119], v[134:137], off offset:1536
	s_and_saveexec_b64 s[98:99], s[10:11]
	s_cbranch_execz .LBB0_1271
	v_lshl_add_u64 v[134:135], s[16:17], 0, v[102:103]
	v_add_co_u32_e32 v134, vcc, 0x9038000, v134
	v_cvt_pk_bf16_f32 v118, v120, v121
	v_cvt_pk_bf16_f32 v119, v114, v115
	v_addc_co_u32_e32 v135, vcc, 0, v135, vcc
	global_store_dwordx2 v[134:135], v[118:119], off offset:1536
.LBB0_1271:
	s_or_b64 exec, exec, s[98:99]
	s_and_saveexec_b64 s[98:99], s[18:19]
	s_cbranch_execz .LBB0_1273
	s_add_u32 s100, s16, s12
	s_addc_u32 s101, s17, s13
	global_store_dword v130, v128, s[100:101] offset:24
.LBB0_1273:
	s_or_b64 exec, exec, s[98:99]
	v_mov_b32_e32 v118, s28
	ds_read_b128 v[134:137], v133 offset:27648
	ds_read_b64 v[118:119], v118 offset:48
	ds_read_b128 v[138:141], v133 offset:27712
	ds_read_b128 v[146:149], v133 offset:29952
	s_waitcnt vmcnt(22) lgkmcnt(3)
	v_mfma_f32_16x16x32_bf16 v[142:145], v[74:77], v[134:137], 0
	s_waitcnt lgkmcnt(2)
	v_add_f32_e32 v118, v128, v118
	v_max_f32_e32 v119, v119, v119
	v_max_f32_e32 v134, v118, v119
	v_sub_f32_e32 v118, v118, v134
	v_mul_f32_e32 v118, 0x3fb8aa3b, v118
	v_exp_f32_e32 v150, v118
	v_mul_f32_e32 v118, 0xbfb8aa3b, v134
	s_waitcnt vmcnt(21) lgkmcnt(1)
	v_mfma_f32_16x16x32_bf16 v[136:139], v[78:81], v[138:141], v[142:145]
	v_mul_f32_e64 v122, v122, v150
	v_mul_f32_e64 v123, v123, v150
	s_nop 0
	ds_read_b128 v[140:143], v133 offset:30016
	s_waitcnt lgkmcnt(1)
	v_mfma_f32_16x16x32_bf16 v[144:147], v[74:77], v[146:149], 0
	v_exp_f32_e32 v148, v118
	v_pk_mul_f32 v[118:119], v[126:127], v[150:151] op_sel_hi:[1,0]
	v_pk_fma_f32 v[122:123], v[138:139], v[148:149], v[122:123] op_sel_hi:[1,0,1]
	v_pk_fma_f32 v[126:127], v[136:137], v[148:149], v[118:119] op_sel_hi:[1,0,1]
	v_mfma_f32_16x16x32_bf16 v[136:139], v[74:77], v[86:89], 0
	s_waitcnt lgkmcnt(0)
	v_mfma_f32_16x16x32_bf16 v[140:143], v[78:81], v[140:143], v[144:147]
	v_mfma_f32_16x16x32_bf16 v[136:139], v[78:81], v[86:89], v[136:139]
	s_nop 6
	v_mul_f32_e64 v118, v148, v142
	v_mul_f32_e64 v119, v148, v143
	v_pk_mul_f32 v[128:129], v[148:149], v[140:141] op_sel_hi:[0,1]
	v_pk_fma_f32 v[118:119], v[116:117], v[150:151], v[118:119] op_sel_hi:[1,0,1]
	v_pk_fma_f32 v[128:129], v[124:125], v[150:151], v[128:129] op_sel_hi:[1,0,1]
	v_pk_mul_f32 v[116:117], v[148:149], v[138:139] op_sel_hi:[0,1]
	v_pk_mul_f32 v[124:125], v[148:149], v[136:137] op_sel_hi:[0,1]
	v_pk_fma_f32 v[116:117], v[114:115], v[150:151], v[116:117] op_sel_hi:[1,0,1]
	v_cvt_pk_bf16_f32 v136, v126, v127
	v_cvt_pk_bf16_f32 v138, v128, v129
	v_cvt_pk_bf16_f32 v137, v122, v123
	v_cvt_pk_bf16_f32 v139, v118, v119
	v_add_co_u32_e32 v114, vcc, 0x9038000, v110
	v_pk_fma_f32 v[120:121], v[120:121], v[150:151], v[124:125] op_sel_hi:[1,0,1]
	v_permlane16_swap_b32_e32 v136, v138
	v_permlane16_swap_b32_e32 v137, v139
	v_addc_co_u32_e32 v115, vcc, 0, v111, vcc
	s_waitcnt lgkmcnt(0)
	s_barrier
	s_add_i32 s24, s29, 15
	s_cmp_gt_u32 s24, 56
	s_cbranch_scc1 .LBB0_1287
	v_add_co_u32_e32 v78, vcc, 0xd038000, v112
	s_nop 1
	v_addc_co_u32_e32 v79, vcc, 0, v113, vcc
	global_load_dwordx4 v[74:77], v[78:79], off
	s_nop 0
	global_load_dwordx4 v[78:81], v[78:79], off offset:64
	s_and_saveexec_b64 s[22:23], s[8:9]
	s_cbranch_execz .LBB0_1286
	v_lshl_add_u64 v[82:83], s[16:17], 0, v[106:107]
	v_add_co_u32_e32 v82, vcc, 0xe038000, v82
	s_nop 1
	v_addc_co_u32_e32 v83, vcc, 0, v83, vcc
	global_load_dwordx4 v[82:85], v[82:83], off

.LBB0_1289:
	s_or_b64 exec, exec, s[24:25]
	global_store_dwordx4 v[114:115], v[136:139], off offset:1792
	s_and_saveexec_b64 s[98:99], s[10:11]
	s_cbranch_execz .LBB0_1281
	v_lshl_add_u64 v[124:125], s[16:17], 0, v[102:103]
	v_add_co_u32_e32 v124, vcc, 0x9040000, v124
	v_cvt_pk_bf16_f32 v114, v120, v121
	v_cvt_pk_bf16_f32 v115, v116, v117
	v_addc_co_u32_e32 v125, vcc, 0, v125, vcc
	global_store_dwordx2 v[124:125], v[114:115], off offset:1792
.LBB0_1281:
	s_or_b64 exec, exec, s[98:99]
	s_and_saveexec_b64 s[98:99], s[18:19]
	s_cbranch_execz .LBB0_1283
	s_add_u32 s100, s16, s12
	s_addc_u32 s101, s17, s13
	global_store_dword v130, v134, s[100:101] offset:28
.LBB0_1283:
	s_or_b64 exec, exec, s[98:99]
	v_mov_b32_e32 v124, s28
	ds_read_b128 v[112:115], v133 offset:32256
	ds_read_b64 v[124:125], v124 offset:56
	ds_read_b128 v[136:139], v133 offset:32320
	ds_read_b128 v[144:147], v133 offset:34560
	s_andn2_b64 vcc, exec, s[22:23]
	s_cmp_lg_u32 s29, 48
	s_cbranch_scc1 .Lch_rlx_22
	s_waitcnt vmcnt(8) lgkmcnt(3)

.LBB0_1807:
	s_lshl_b32 s8, s56, 5
	s_lshl_b32 s9, s20, 8
	v_lshrrev_b32_e32 v130, 1, v237
	s_or_b32 s8, s9, s8
	v_and_or_b32 v154, v130, 24, s8
	s_ashr_i32 s8, s14, 31
	s_lshr_b32 s8, s8, 28
	s_add_i32 s8, s14, s8
	s_ashr_i32 s8, s8, 4
	v_ashrrev_i32_e32 v155, 31, v154
	v_mov_b32_e32 v130, 0x2400
	v_mad_i64_i32 v[130:131], s[8:9], s8, v130, v[154:155]
	v_lshl_add_u64 v[156:157], v[130:131], 2, s[18:19]
	s_mov_b32 s10, 0x105000
	v_add_co_u32_e32 v130, vcc, s10, v156
	s_mov_b64 s[8:9], 0x105000
	s_nop 0
	v_addc_co_u32_e32 v131, vcc, 0, v157, vcc
	s_barrier
	global_load_dwordx4 v[142:145], v[130:131], off
	v_lshl_add_u64 v[130:131], v[156:157], 0, s[8:9]
	global_load_dwordx4 v[138:141], v[130:131], off offset:16
	global_load_dwordx4 v[134:137], v[130:131], off offset:512
	s_nop 0
	global_load_dwordx4 v[130:133], v[130:131], off offset:528
	s_bfe_u32 s8, s60, 0x10006
	s_lshl_b32 s12, s8, 10
	s_lshl_b32 s24, s14, 8
	s_add_i32 s12, s12, s67
	s_add_i32 s10, s24, s57
	s_add_i32 s12, s12, 0
	s_mov_b32 s9, 0x10000
	s_bitcmp0_b32 s60, 7
	v_add_u32_e32 v161, s12, v239
	s_cselect_b32 s12, s9, 0x18000
	s_lshl_b32 s9, s56, 14
	s_or_b32 s13, s57, 16
	s_and_b32 s9, s9, 0x8000
	v_add_u32_e32 v146, s12, v161
	v_or_b32_e32 v147, s13, v199
	v_add_u32_e32 v150, s9, v161
	v_lshlrev_b32_e32 v158, 6, v147
	v_lshlrev_b32_e32 v159, 2, v147
	ds_read_b128 v[146:149], v146
	ds_read_b128 v[150:153], v150
	s_lshr_b32 s13, s13, 3
	s_or_b32 s13, s13, s8
	s_movk_i32 s11, 0x3c0
	s_lshl_b32 s13, s13, 10
	v_and_or_b32 v158, v158, s11, v238
	v_and_b32_e32 v159, 32, v159
	s_add_i32 s13, s13, 0
	v_xad_u32 v159, v158, v159, s13
	s_waitcnt lgkmcnt(0)
	v_lshlrev_b32_e32 v162, 16, v146
	v_and_b32_e32 v163, 0xffff0000, v146
	v_lshlrev_b32_e32 v146, 16, v147
	v_and_b32_e32 v147, 0xffff0000, v147
	v_lshlrev_b32_e32 v164, 16, v148
	v_and_b32_e32 v165, 0xffff0000, v148
	v_lshlrev_b32_e32 v148, 16, v149
	v_and_b32_e32 v149, 0xffff0000, v149
	v_lshlrev_b32_e32 v166, 16, v150
	v_and_b32_e32 v167, 0xffff0000, v150
	v_lshlrev_b32_e32 v150, 16, v151
	v_and_b32_e32 v151, 0xffff0000, v151
	v_lshlrev_b32_e32 v168, 16, v152
	v_and_b32_e32 v169, 0xffff0000, v152
	v_lshlrev_b32_e32 v152, 16, v153
	v_and_b32_e32 v153, 0xffff0000, v153
	v_add_u32_e32 v158, s12, v159
	s_or_b32 s13, s57, 32
	s_waitcnt vmcnt(0)
	v_pk_fma_f32 v[122:123], v[122:123], v[138:139], v[164:165]
	v_pk_fma_f32 v[128:129], v[128:129], v[144:145], v[146:147]
	v_pk_fma_f32 v[126:127], v[126:127], v[142:143], v[162:163]
	v_pk_fma_f32 v[124:125], v[124:125], v[140:141], v[148:149]
	v_pk_fma_f32 v[114:115], v[114:115], v[134:135], v[166:167]
	v_pk_fma_f32 v[116:117], v[116:117], v[136:137], v[150:151]
	v_pk_fma_f32 v[106:107], v[106:107], v[130:131], v[168:169]
	v_pk_fma_f32 v[108:109], v[108:109], v[132:133], v[152:153]
	v_add_u32_e32 v150, s9, v159
	ds_read_b128 v[146:149], v158
	ds_read_b128 v[150:153], v150
	s_waitcnt lgkmcnt(1)
	v_lshlrev_b32_e32 v162, 16, v146
	v_and_b32_e32 v163, 0xffff0000, v146
	v_lshlrev_b32_e32 v146, 16, v147
	v_and_b32_e32 v147, 0xffff0000, v147
	v_pk_fma_f32 v[120:121], v[120:121], v[144:145], v[146:147]
	s_waitcnt lgkmcnt(0)
	v_lshlrev_b32_e32 v146, 16, v150
	v_and_b32_e32 v147, 0xffff0000, v150
	v_pk_fma_f32 v[102:103], v[102:103], v[134:135], v[146:147]
	v_or_b32_e32 v146, s13, v199
	s_lshr_b32 s13, s13, 3
	s_or_b32 s13, s13, s8
	v_lshlrev_b32_e32 v164, 16, v148
	v_and_b32_e32 v165, 0xffff0000, v148
	v_lshlrev_b32_e32 v148, 16, v149
	v_and_b32_e32 v149, 0xffff0000, v149
	v_lshlrev_b32_e32 v147, 6, v146
	s_lshl_b32 s13, s13, 10
	v_lshlrev_b32_e32 v146, 2, v146
	v_pk_fma_f32 v[112:113], v[112:113], v[140:141], v[148:149]
	v_lshlrev_b32_e32 v148, 16, v151
	v_and_b32_e32 v149, 0xffff0000, v151
	v_lshlrev_b32_e32 v150, 16, v152
	v_and_b32_e32 v151, 0xffff0000, v152
	v_lshlrev_b32_e32 v152, 16, v153
	v_and_b32_e32 v153, 0xffff0000, v153
	v_and_or_b32 v147, v147, s11, v238
	v_and_b32_e32 v146, 32, v146
	s_add_i32 s13, s13, 0
	v_pk_fma_f32 v[118:119], v[118:119], v[142:143], v[162:163]
	v_pk_fma_f32 v[110:111], v[110:111], v[138:139], v[164:165]
	v_pk_fma_f32 v[104:105], v[104:105], v[136:137], v[148:149]
	v_pk_fma_f32 v[100:101], v[100:101], v[132:133], v[152:153]
	v_pk_fma_f32 v[98:99], v[98:99], v[130:131], v[150:151]
	v_xad_u32 v160, v147, v146, s13
	v_add_u32_e32 v146, s12, v160
	ds_read_b128 v[146:149], v146
	v_add_u32_e32 v150, s9, v160
	ds_read_b128 v[150:153], v150
	s_or_b32 s13, s57, 48
	s_waitcnt lgkmcnt(1)
	v_lshlrev_b32_e32 v162, 16, v146
	v_and_b32_e32 v163, 0xffff0000, v146
	v_lshlrev_b32_e32 v146, 16, v147
	v_and_b32_e32 v147, 0xffff0000, v147
	v_pk_fma_f32 v[96:97], v[96:97], v[144:145], v[146:147]
	s_waitcnt lgkmcnt(0)
	v_lshlrev_b32_e32 v146, 16, v150
	v_and_b32_e32 v147, 0xffff0000, v150
	v_pk_fma_f32 v[86:87], v[86:87], v[134:135], v[146:147]
	v_or_b32_e32 v146, s13, v199
	s_lshr_b32 s13, s13, 3
	s_or_b32 s8, s13, s8
	v_lshlrev_b32_e32 v147, 6, v146
	s_lshl_b32 s8, s8, 10
	v_lshlrev_b32_e32 v146, 2, v146
	v_lshlrev_b32_e32 v164, 16, v148
	v_and_b32_e32 v165, 0xffff0000, v148
	v_lshlrev_b32_e32 v148, 16, v149
	v_and_b32_e32 v149, 0xffff0000, v149
	v_and_or_b32 v147, v147, s11, v238
	v_and_b32_e32 v146, 32, v146
	s_add_i32 s8, s8, 0
	v_pk_fma_f32 v[92:93], v[92:93], v[140:141], v[148:149]
	v_lshlrev_b32_e32 v148, 16, v151
	v_and_b32_e32 v149, 0xffff0000, v151
	v_lshlrev_b32_e32 v150, 16, v152
	v_and_b32_e32 v151, 0xffff0000, v152
	v_lshlrev_b32_e32 v152, 16, v153
	v_and_b32_e32 v153, 0xffff0000, v153
	v_xad_u32 v158, v147, v146, s8
	v_pk_fma_f32 v[94:95], v[94:95], v[142:143], v[162:163]
	v_pk_fma_f32 v[90:91], v[90:91], v[138:139], v[164:165]
	v_pk_fma_f32 v[88:89], v[88:89], v[136:137], v[148:149]
	v_pk_fma_f32 v[84:85], v[84:85], v[132:133], v[152:153]
	v_pk_fma_f32 v[82:83], v[82:83], v[130:131], v[150:151]
	v_add_u32_e32 v146, s12, v158
	ds_read_b128 v[146:149], v146
	v_add_u32_e32 v150, s9, v158
	ds_read_b128 v[150:153], v150
	s_cmp_gt_u32 s56, 1
	s_cselect_b64 s[8:9], -1, 0
	s_waitcnt lgkmcnt(1)
	v_lshlrev_b32_e32 v162, 16, v146
	v_and_b32_e32 v163, 0xffff0000, v146
	v_lshlrev_b32_e32 v146, 16, v147
	v_and_b32_e32 v147, 0xffff0000, v147
	v_lshlrev_b32_e32 v164, 16, v148
	v_and_b32_e32 v165, 0xffff0000, v148
	v_lshlrev_b32_e32 v148, 16, v149
	v_and_b32_e32 v149, 0xffff0000, v149
	v_pk_fma_f32 v[80:81], v[80:81], v[144:145], v[146:147]
	v_pk_fma_f32 v[76:77], v[76:77], v[140:141], v[148:149]
	s_waitcnt lgkmcnt(0)
	v_lshlrev_b32_e32 v146, 16, v150
	v_and_b32_e32 v147, 0xffff0000, v150
	v_lshlrev_b32_e32 v148, 16, v151
	v_and_b32_e32 v149, 0xffff0000, v151
	v_lshlrev_b32_e32 v150, 16, v152
	v_and_b32_e32 v151, 0xffff0000, v152
	v_lshlrev_b32_e32 v152, 16, v153
	v_and_b32_e32 v153, 0xffff0000, v153
	s_cmp_lt_u32 s56, 2
	s_mov_b32 s11, 0x14000
	v_pk_fma_f32 v[78:79], v[78:79], v[142:143], v[162:163]
	v_pk_fma_f32 v[74:75], v[74:75], v[138:139], v[164:165]
	v_pk_fma_f32 v[72:73], v[72:73], v[136:137], v[148:149]
	v_pk_fma_f32 v[70:71], v[70:71], v[134:135], v[146:147]
	v_pk_fma_f32 v[68:69], v[68:69], v[132:133], v[152:153]
	v_pk_fma_f32 v[66:67], v[66:67], v[130:131], v[150:151]
	s_cselect_b32 s12, s11, 0x1c000
	v_add_u32_e32 v146, s12, v161
	ds_read_b128 v[150:153], v146
	v_or_b32_e32 v162, s10, v199
	s_and_b64 vcc, exec, s[8:9]
	s_cbranch_vccz .LBB0_1826
	v_add_u32_e32 v146, 0x80, v162
	v_ashrrev_i32_e32 v147, 31, v146
	v_lshlrev_b64 v[146:147], 11, v[146:147]
	v_lshl_add_u64 v[146:147], s[16:17], 0, v[146:147]
	v_lshl_add_u64 v[146:147], v[154:155], 1, v[146:147]
	s_mov_b64 s[100:101], 0x8000
	v_lshl_add_u64 v[216:217], v[146:147], 0, s[100:101]
	global_load_dwordx4 v[200:203], v[216:217], off offset:256
	v_lshl_add_u64 v[216:217], v[216:217], 0, s[100:101]
	global_load_dwordx4 v[204:207], v[216:217], off offset:256
	v_lshl_add_u64 v[216:217], v[216:217], 0, s[100:101]
	global_load_dwordx4 v[208:211], v[216:217], off offset:256
	global_load_dwordx4 v[146:149], v[146:147], off offset:256
	s_cbranch_execz .LBB0_1827
	s_branch .LBB0_1828

.LBB0_1828:
	s_waitcnt lgkmcnt(0)
	v_lshlrev_b32_e32 v164, 16, v150
	v_and_b32_e32 v165, 0xffff0000, v150
	v_lshlrev_b32_e32 v150, 16, v151
	v_and_b32_e32 v151, 0xffff0000, v151
	v_lshlrev_b32_e32 v166, 16, v152
	v_and_b32_e32 v167, 0xffff0000, v152
	v_lshlrev_b32_e32 v152, 16, v153
	v_and_b32_e32 v153, 0xffff0000, v153
	v_pk_fma_f32 v[64:65], v[64:65], v[144:145], v[150:151]
	v_pk_fma_f32 v[60:61], v[60:61], v[140:141], v[152:153]
	s_waitcnt vmcnt(0)
	v_lshlrev_b32_e32 v150, 16, v146
	v_and_b32_e32 v151, 0xffff0000, v146
	v_lshlrev_b32_e32 v146, 16, v147
	v_and_b32_e32 v147, 0xffff0000, v147
	v_lshlrev_b32_e32 v152, 16, v148
	v_and_b32_e32 v153, 0xffff0000, v148
	v_lshlrev_b32_e32 v148, 16, v149
	v_and_b32_e32 v149, 0xffff0000, v149
	v_pk_fma_f32 v[62:63], v[62:63], v[142:143], v[164:165]
	v_pk_fma_f32 v[58:59], v[58:59], v[138:139], v[166:167]
	v_pk_fma_f32 v[56:57], v[56:57], v[136:137], v[146:147]
	v_pk_fma_f32 v[54:55], v[54:55], v[134:135], v[150:151]
	v_pk_fma_f32 v[52:53], v[52:53], v[132:133], v[148:149]
	v_pk_fma_f32 v[50:51], v[50:51], v[130:131], v[152:153]
	v_add_u32_e32 v146, s12, v159
	ds_read_b128 v[150:153], v146
	s_and_b64 vcc, exec, s[8:9]
	s_cbranch_vccz .LBB0_1830
	v_mov_b32_e32 v146, v200
	v_mov_b32_e32 v147, v201
	v_mov_b32_e32 v148, v202
	v_mov_b32_e32 v149, v203
	s_cbranch_execz .LBB0_1831
	s_branch .LBB0_1832

.LBB0_1832:
	s_waitcnt lgkmcnt(0)
	v_lshlrev_b32_e32 v164, 16, v150
	v_and_b32_e32 v165, 0xffff0000, v150
	v_lshlrev_b32_e32 v150, 16, v151
	v_and_b32_e32 v151, 0xffff0000, v151
	v_lshlrev_b32_e32 v166, 16, v152
	v_and_b32_e32 v167, 0xffff0000, v152
	v_lshlrev_b32_e32 v152, 16, v153
	v_and_b32_e32 v153, 0xffff0000, v153
	v_pk_fma_f32 v[48:49], v[48:49], v[144:145], v[150:151]
	v_pk_fma_f32 v[44:45], v[44:45], v[140:141], v[152:153]
	s_waitcnt vmcnt(0)
	v_lshlrev_b32_e32 v150, 16, v146
	v_and_b32_e32 v151, 0xffff0000, v146
	v_lshlrev_b32_e32 v146, 16, v147
	v_and_b32_e32 v147, 0xffff0000, v147
	v_lshlrev_b32_e32 v152, 16, v148
	v_and_b32_e32 v153, 0xffff0000, v148
	v_lshlrev_b32_e32 v148, 16, v149
	v_and_b32_e32 v149, 0xffff0000, v149
	v_pk_fma_f32 v[46:47], v[46:47], v[142:143], v[164:165]
	v_pk_fma_f32 v[42:43], v[42:43], v[138:139], v[166:167]
	v_pk_fma_f32 v[40:41], v[40:41], v[136:137], v[146:147]
	v_pk_fma_f32 v[38:39], v[38:39], v[134:135], v[150:151]
	v_pk_fma_f32 v[36:37], v[36:37], v[132:133], v[148:149]
	v_pk_fma_f32 v[34:35], v[34:35], v[130:131], v[152:153]
	v_add_u32_e32 v146, s12, v160
	ds_read_b128 v[150:153], v146
	s_and_b64 vcc, exec, s[8:9]
	s_cbranch_vccz .LBB0_1834
	v_mov_b32_e32 v146, v204
	v_mov_b32_e32 v147, v205
	v_mov_b32_e32 v148, v206
	v_mov_b32_e32 v149, v207
	s_cbranch_execz .LBB0_1835
	s_branch .LBB0_1836

.LBB0_1836:
	s_waitcnt lgkmcnt(0)
	v_lshlrev_b32_e32 v160, 16, v150
	v_and_b32_e32 v161, 0xffff0000, v150
	v_lshlrev_b32_e32 v150, 16, v151
	v_and_b32_e32 v151, 0xffff0000, v151
	v_lshlrev_b32_e32 v164, 16, v152
	v_and_b32_e32 v165, 0xffff0000, v152
	v_lshlrev_b32_e32 v152, 16, v153
	v_and_b32_e32 v153, 0xffff0000, v153
	v_pk_fma_f32 v[32:33], v[32:33], v[144:145], v[150:151]
	v_pk_fma_f32 v[28:29], v[28:29], v[140:141], v[152:153]
	s_waitcnt vmcnt(0)
	v_lshlrev_b32_e32 v150, 16, v146
	v_and_b32_e32 v151, 0xffff0000, v146
	v_lshlrev_b32_e32 v146, 16, v147
	v_and_b32_e32 v147, 0xffff0000, v147
	v_lshlrev_b32_e32 v152, 16, v148
	v_and_b32_e32 v153, 0xffff0000, v148
	v_lshlrev_b32_e32 v148, 16, v149
	v_and_b32_e32 v149, 0xffff0000, v149
	v_pk_fma_f32 v[30:31], v[30:31], v[142:143], v[160:161]
	v_pk_fma_f32 v[26:27], v[26:27], v[138:139], v[164:165]
	v_pk_fma_f32 v[24:25], v[24:25], v[136:137], v[146:147]
	v_pk_fma_f32 v[22:23], v[22:23], v[134:135], v[150:151]
	v_pk_fma_f32 v[20:21], v[20:21], v[132:133], v[148:149]
	v_pk_fma_f32 v[18:19], v[18:19], v[130:131], v[152:153]
	v_add_u32_e32 v146, s12, v158
	ds_read_b128 v[150:153], v146
	s_and_b64 vcc, exec, s[8:9]
	s_cbranch_vccz .LBB0_1838
	v_mov_b32_e32 v146, v208
	v_mov_b32_e32 v147, v209
	v_mov_b32_e32 v148, v210
	v_mov_b32_e32 v149, v211
	s_cbranch_execz .LBB0_1839
	s_branch .LBB0_1840
